# GU epilogue: row-statistics (ssq) loads prefetched after the last K-iteration wait; setprio 0 moved after the post-MFMA barrier; mid-block setprio pairs removed in all K-loops
# baseline (speedup 1.0000x reference)
; #define PG8_STAGE(bufoff, gbase, voff) do { _Pragma("unroll") for (int _i = 0; _i < 2; ++_i) \
;         __builtin_amdgcn_global_load_lds((const unsigned*)((const char*)(gbase) + (voff)[_i]), (PG8_LAS unsigned*)(lds + (bufoff) + ldsw + _i * 8192), 16, 0, 0); } while (0)
; #define PG8_LDA(dst, b, h) do { _Pragma("unroll") for (int m = 0; m < 4; ++m) _Pragma("unroll") for (int k = 0; k < 2; ++k) dst[m][k] = *(const PG8_LAS bf16x8*)(lds + PG8_SA(b, h) + aoff + m * 2048 + k * 1024); } while (0)
; #define PG8_LDB(dst, b, h) do { _Pragma("unroll") for (int n = 0; n < 2; ++n) _Pragma("unroll") for (int k = 0; k < 2; ++k) dst[n][k] = *(const PG8_LAS bf16x8*)(lds + PG8_SB(b, h) + boff + n * 2048 + k * 1024); } while (0)
; #define PG8_MMA(ai, bj, At, Bt) do { __builtin_amdgcn_s_setprio(1); _Pragma("unroll") for (int m = 0; m < 4; ++m) _Pragma("unroll") for (int n = 0; n < 2; ++n) _Pragma("unroll") for (int k = 0; k < 2; ++k) \
;         acc[ai][bj][m][n] = __builtin_amdgcn_mfma_f32_16x16x32_bf16(Bt[n][k], At[m][k], acc[ai][bj][m][n], 0, 0, 0); __builtin_amdgcn_s_setprio(0); } while (0)
; #define PG8_WAIT_V(n) asm volatile("s_waitcnt vmcnt(" #n ")" ::: "memory")
; #define PG8_WAIT_L(n) asm volatile("s_waitcnt lgkmcnt(" #n ")" ::: "memory")
; template <class Epi, class Sched, bool ALIGN_EPI = false, bool SP2 = true>
; __device__ __forceinline__ void gemm_phase(PG8_LAS unsigned char* lds, const Gemm g, const Sched& S, const Epi& E) {
;     ...
;             const bool last = (t == nt - 2);
;             const char* a1 = cA + (size_t)(t + 1) * kstepA;
;             const char* a2 = last ? nA : cA + (size_t)(t + 2) * kstepA; const char* b2 = last ? nB : cB + (size_t)(t + 2) * kstep;
;             const char* a3 = a2 + kstepA; const char* b3 = b2 + kstep;
;             if (last && has_next) S.a_ready(nxt);
;             if constexpr (SP2) {
;             PG8_LDB(B0, 0, 0); PG8_LDB(B1, 0, 1); PG8_SCHED; PG8_LDA(At, 0, 0); PG8_STAGE(PG8_SA(1, 1), a1 + hstepA, voffA);
;             PG8_WAIT_V(8); PG8_WAIT_L(0); PG8_BAR; PG8_MMA(0, 0, At, B0); PG8_MMA(0, 1, At, B1); PG8_BAR; PG8_SCHED;
;             PG8_LDA(At, 0, 1); PG8_STAGE(PG8_SB(0, 0), b2, voffB); PG8_STAGE(PG8_SB(0, 1), b2 + hstep, voffB); PG8_STAGE(PG8_SA(0, 0), a2, voffA);
;             PG8_WAIT_V(8); PG8_WAIT_L(0); PG8_BAR; PG8_MMA(1, 0, At, B0); PG8_MMA(1, 1, At, B1); PG8_BAR; PG8_SCHED;
.LBB0_128:
	s_add_u32 s14, s46, 0xfffc0080
	s_addc_u32 s15, s47, -1
	s_add_i32 s70, 0, 0x10000
	s_cmp_eq_u32 s60, 12
	s_cselect_b32 s51, s17, s15
	s_cselect_b32 s50, s39, s14
	v_add_u32_e32 v141, s70, v147
	s_cselect_b32 s49, s25, s7
	s_cselect_b32 s48, s59, s6
	s_add_i32 s71, 0, 0x14000
	ds_read_b128 v[152:155], v141
	ds_read_b128 v[156:159], v141 offset:1024
	ds_read_b128 v[160:163], v141 offset:2048
	ds_read_b128 v[164:167], v141 offset:3072
	v_add_u32_e32 v141, s71, v147
	ds_read_b128 v[168:171], v141
	ds_read_b128 v[172:175], v141 offset:1024
	ds_read_b128 v[176:179], v141 offset:2048
	ds_read_b128 v[180:183], v141 offset:3072
	s_add_u32 s14, s6, 0x3ff80
	s_addc_u32 s15, s7, 0
	v_lshl_add_u64 v[148:149], s[14:15], 0, v[132:133]
	s_add_i32 m0, s28, 0x1c000
	ds_read_b128 v[184:187], v150
	ds_read_b128 v[188:191], v150 offset:1024
	ds_read_b128 v[200:203], v150 offset:2048
	ds_read_b128 v[204:207], v150 offset:3072
	ds_read_b128 v[208:211], v150 offset:4096
	ds_read_b128 v[212:215], v150 offset:5120
	ds_read_b128 v[216:219], v150 offset:6144
	ds_read_b128 v[220:223], v150 offset:7168
	global_load_lds_dwordx4 v[148:149], off
	v_lshl_add_u64 v[148:149], s[14:15], 0, v[128:129]
	s_add_i32 m0, s28, 0x1e000
	s_nop 0
	global_load_lds_dwordx4 v[148:149], off
	v_lshl_add_u64 v[148:149], s[46:47], 0, v[136:137]
	s_add_i32 m0, s29, 0xc000
	s_nop 0
	global_load_lds_dwordx4 v[148:149], off
	v_lshl_add_u64 v[148:149], s[46:47], 0, v[138:139]
	s_add_i32 m0, s29, 0xe000
	s_nop 0
	global_load_lds_dwordx4 v[148:149], off
	s_waitcnt vmcnt(8)
	s_waitcnt lgkmcnt(0)
	s_setprio 1
	s_barrier
	v_mfma_f32_16x16x32_bf16 v[120:123], v[152:155], v[184:187], v[120:123]
	v_mfma_f32_16x16x32_bf16 v[112:115], v[160:163], v[184:187], v[112:115]
	v_mfma_f32_16x16x32_bf16 v[108:111], v[152:155], v[200:203], v[108:111]
	v_mfma_f32_16x16x32_bf16 v[96:99], v[160:163], v[200:203], v[96:99]
	v_mfma_f32_16x16x32_bf16 v[92:95], v[152:155], v[208:211], v[92:95]
	v_mfma_f32_16x16x32_bf16 v[80:83], v[160:163], v[208:211], v[80:83]
	v_mfma_f32_16x16x32_bf16 v[76:79], v[152:155], v[216:219], v[76:79]
	v_mfma_f32_16x16x32_bf16 v[64:67], v[160:163], v[216:219], v[64:67]
	v_mfma_f32_16x16x32_bf16 v[120:123], v[156:159], v[188:191], v[120:123]
	v_mfma_f32_16x16x32_bf16 v[112:115], v[164:167], v[188:191], v[112:115]
	v_mfma_f32_16x16x32_bf16 v[108:111], v[156:159], v[204:207], v[108:111]
	v_mfma_f32_16x16x32_bf16 v[96:99], v[164:167], v[204:207], v[96:99]
	v_mfma_f32_16x16x32_bf16 v[92:95], v[156:159], v[212:215], v[92:95]
	v_mfma_f32_16x16x32_bf16 v[80:83], v[164:167], v[212:215], v[80:83]
	v_mfma_f32_16x16x32_bf16 v[76:79], v[156:159], v[220:223], v[76:79]
	v_mfma_f32_16x16x32_bf16 v[64:67], v[164:167], v[220:223], v[64:67]
	v_mfma_f32_16x16x32_bf16 v[124:127], v[168:171], v[184:187], v[124:127]
	v_mfma_f32_16x16x32_bf16 v[116:119], v[176:179], v[184:187], v[116:119]
	v_mfma_f32_16x16x32_bf16 v[104:107], v[168:171], v[200:203], v[104:107]
	v_mfma_f32_16x16x32_bf16 v[100:103], v[176:179], v[200:203], v[100:103]
	v_mfma_f32_16x16x32_bf16 v[88:91], v[168:171], v[208:211], v[88:91]
	v_mfma_f32_16x16x32_bf16 v[84:87], v[176:179], v[208:211], v[84:87]
	v_mfma_f32_16x16x32_bf16 v[72:75], v[168:171], v[216:219], v[72:75]
	v_mfma_f32_16x16x32_bf16 v[68:71], v[176:179], v[216:219], v[68:71]
	v_mfma_f32_16x16x32_bf16 v[124:127], v[172:175], v[188:191], v[124:127]
	v_mfma_f32_16x16x32_bf16 v[116:119], v[180:183], v[188:191], v[116:119]
	v_mfma_f32_16x16x32_bf16 v[104:107], v[172:175], v[204:207], v[104:107]
	v_mfma_f32_16x16x32_bf16 v[100:103], v[180:183], v[204:207], v[100:103]
	v_mfma_f32_16x16x32_bf16 v[88:91], v[172:175], v[212:215], v[88:91]
	v_mfma_f32_16x16x32_bf16 v[84:87], v[180:183], v[212:215], v[84:87]
	v_mfma_f32_16x16x32_bf16 v[72:75], v[172:175], v[220:223], v[72:75]
	v_mfma_f32_16x16x32_bf16 v[68:71], v[180:183], v[220:223], v[68:71]
	s_barrier
	s_setprio 0
	s_add_i32 s14, s70, s28
	v_lshl_add_u64 v[148:149], s[48:49], 0, v[132:133]
	s_mov_b32 m0, s14
	ds_read_b128 v[184:187], v150 offset:16384
	ds_read_b128 v[188:191], v150 offset:17408
	ds_read_b128 v[200:203], v150 offset:18432
	ds_read_b128 v[204:207], v150 offset:19456
	ds_read_b128 v[208:211], v150 offset:20480
	ds_read_b128 v[212:215], v150 offset:21504
	ds_read_b128 v[216:219], v150 offset:22528
	ds_read_b128 v[220:223], v150 offset:23552
	global_load_lds_dwordx4 v[148:149], off
	s_add_i32 m0, s14, 0x2000
	v_lshl_add_u64 v[224:225], s[48:49], 0, v[128:129]
	global_load_lds_dwordx4 v[224:225], off
	v_lshl_add_u64 v[234:235], s[50:51], 0, v[130:131]
	v_lshl_add_u64 v[226:227], s[50:51], 0, v[134:135]
	s_mov_b32 m0, s29
	s_nop 0
	global_load_lds_dwordx4 v[226:227], off
	s_mov_b32 m0, s30
	s_nop 0
	global_load_lds_dwordx4 v[234:235], off
	s_waitcnt vmcnt(6)
	s_waitcnt lgkmcnt(0)
	s_setprio 1
	s_barrier
; #define PG8_STAGE(bufoff, gbase, voff) do { _Pragma("unroll") for (int _i = 0; _i < 2; ++_i) \
;         __builtin_amdgcn_global_load_lds((const unsigned*)((const char*)(gbase) + (voff)[_i]), (PG8_LAS unsigned*)(lds + (bufoff) + ldsw + _i * 8192), 16, 0, 0); } while (0)
; #define PG8_LDA(dst, b, h) do { _Pragma("unroll") for (int m = 0; m < 4; ++m) _Pragma("unroll") for (int k = 0; k < 2; ++k) dst[m][k] = *(const PG8_LAS bf16x8*)(lds + PG8_SA(b, h) + aoff + m * 2048 + k * 1024); } while (0)
; #define PG8_LDB(dst, b, h) do { _Pragma("unroll") for (int n = 0; n < 2; ++n) _Pragma("unroll") for (int k = 0; k < 2; ++k) dst[n][k] = *(const PG8_LAS bf16x8*)(lds + PG8_SB(b, h) + boff + n * 2048 + k * 1024); } while (0)
; #define PG8_MMA(ai, bj, At, Bt) do { __builtin_amdgcn_s_setprio(1); _Pragma("unroll") for (int m = 0; m < 4; ++m) _Pragma("unroll") for (int n = 0; n < 2; ++n) _Pragma("unroll") for (int k = 0; k < 2; ++k) \
;         acc[ai][bj][m][n] = __builtin_amdgcn_mfma_f32_16x16x32_bf16(Bt[n][k], At[m][k], acc[ai][bj][m][n], 0, 0, 0); __builtin_amdgcn_s_setprio(0); } while (0)
; #define PG8_WAIT_V(n) asm volatile("s_waitcnt vmcnt(" #n ")" ::: "memory")
; #define PG8_WAIT_L(n) asm volatile("s_waitcnt lgkmcnt(" #n ")" ::: "memory")
; #define PG8_BAR __builtin_amdgcn_s_barrier()
; #define PG8_SCHED __builtin_amdgcn_sched_barrier(0)
; template <class Epi, class Sched, bool ALIGN_EPI = false, bool SP2 = true>
; __device__ __forceinline__ void gemm_phase(PG8_LAS unsigned char* lds, const Gemm g, const Sched& S, const Epi& E) {
;     ...
;             PG8_WAIT_V(8); PG8_WAIT_L(0); PG8_BAR; PG8_MMA(1, 0, At, B0); PG8_MMA(1, 1, At, B1); PG8_BAR; PG8_SCHED;
;             PG8_LDB(B0, 1, 0); PG8_LDB(B1, 1, 1); PG8_SCHED; PG8_LDA(At, 1, 0); PG8_STAGE(PG8_SA(0, 1), a2 + hstepA, voffA);
;             PG8_WAIT_V(8); PG8_WAIT_L(0); PG8_BAR; PG8_MMA(0, 0, At, B0); PG8_MMA(0, 1, At, B1); PG8_BAR; PG8_SCHED;
;             PG8_LDA(At, 1, 1); PG8_STAGE(PG8_SB(1, 0), b3, voffB); PG8_STAGE(PG8_SB(1, 1), b3 + hstep, voffB); PG8_STAGE(PG8_SA(1, 0), a3, voffA);
;             PG8_WAIT_V(8); PG8_WAIT_L(0); PG8_BAR; PG8_MMA(1, 0, At, B0); PG8_MMA(1, 1, At, B1); PG8_BAR; PG8_SCHED;
	v_mfma_f32_16x16x32_bf16 v[60:63], v[152:155], v[184:187], v[60:63]
	v_mfma_f32_16x16x32_bf16 v[48:51], v[160:163], v[184:187], v[48:51]
	v_mfma_f32_16x16x32_bf16 v[44:47], v[152:155], v[200:203], v[44:47]
	v_mfma_f32_16x16x32_bf16 v[32:35], v[160:163], v[200:203], v[32:35]
	v_mfma_f32_16x16x32_bf16 v[28:31], v[152:155], v[208:211], v[28:31]
	v_mfma_f32_16x16x32_bf16 v[16:19], v[160:163], v[208:211], v[16:19]
	v_mfma_f32_16x16x32_bf16 v[12:15], v[152:155], v[216:219], v[12:15]
	v_mfma_f32_16x16x32_bf16 v[4:7], v[160:163], v[216:219], v[4:7]
	v_mfma_f32_16x16x32_bf16 v[60:63], v[156:159], v[188:191], v[60:63]
	v_mfma_f32_16x16x32_bf16 v[48:51], v[164:167], v[188:191], v[48:51]
	v_mfma_f32_16x16x32_bf16 v[44:47], v[156:159], v[204:207], v[44:47]
	v_mfma_f32_16x16x32_bf16 v[32:35], v[164:167], v[204:207], v[32:35]
	v_mfma_f32_16x16x32_bf16 v[28:31], v[156:159], v[212:215], v[28:31]
	v_mfma_f32_16x16x32_bf16 v[16:19], v[164:167], v[212:215], v[16:19]
	v_mfma_f32_16x16x32_bf16 v[12:15], v[156:159], v[220:223], v[12:15]
	v_mfma_f32_16x16x32_bf16 v[4:7], v[164:167], v[220:223], v[4:7]
	v_mfma_f32_16x16x32_bf16 v[56:59], v[168:171], v[184:187], v[56:59]
	v_mfma_f32_16x16x32_bf16 v[52:55], v[176:179], v[184:187], v[52:55]
	v_mfma_f32_16x16x32_bf16 v[40:43], v[168:171], v[200:203], v[40:43]
	v_mfma_f32_16x16x32_bf16 v[36:39], v[176:179], v[200:203], v[36:39]
	v_mfma_f32_16x16x32_bf16 v[24:27], v[168:171], v[208:211], v[24:27]
	v_mfma_f32_16x16x32_bf16 v[20:23], v[176:179], v[208:211], v[20:23]
	v_mfma_f32_16x16x32_bf16 v[8:11], v[168:171], v[216:219], v[8:11]
	v_mfma_f32_16x16x32_bf16 v[0:3], v[176:179], v[216:219], v[0:3]
	v_mfma_f32_16x16x32_bf16 v[56:59], v[172:175], v[188:191], v[56:59]
	v_mfma_f32_16x16x32_bf16 v[52:55], v[180:183], v[188:191], v[52:55]
	v_mfma_f32_16x16x32_bf16 v[40:43], v[172:175], v[204:207], v[40:43]
	v_mfma_f32_16x16x32_bf16 v[36:39], v[180:183], v[204:207], v[36:39]
	v_mfma_f32_16x16x32_bf16 v[24:27], v[172:175], v[212:215], v[24:27]
	v_mfma_f32_16x16x32_bf16 v[20:23], v[180:183], v[212:215], v[20:23]
	v_mfma_f32_16x16x32_bf16 v[8:11], v[172:175], v[220:223], v[8:11]
	v_mfma_f32_16x16x32_bf16 v[0:3], v[180:183], v[220:223], v[0:3]
	s_barrier
	s_setprio 0
	s_add_i32 s70, 0, 0x18000
	v_add_u32_e32 v141, s70, v147
	s_add_i32 s71, 0, 0x1c000
	ds_read_b128 v[152:155], v141
	ds_read_b128 v[156:159], v141 offset:1024
	ds_read_b128 v[160:163], v141 offset:2048
	ds_read_b128 v[164:167], v141 offset:3072
	v_add_u32_e32 v141, s71, v147
	ds_read_b128 v[168:171], v141
	ds_read_b128 v[172:175], v141 offset:1024
	ds_read_b128 v[176:179], v141 offset:2048
	ds_read_b128 v[180:183], v141 offset:3072
	s_add_u32 s14, s48, 0x40000
	s_addc_u32 s15, s49, 0
	s_add_i32 m0, s28, 0x14000
	v_lshl_add_u64 v[236:237], s[14:15], 0, v[132:133]
	ds_read_b128 v[184:187], v150 offset:32768
	ds_read_b128 v[188:191], v150 offset:33792
	ds_read_b128 v[200:203], v150 offset:34816
	ds_read_b128 v[204:207], v150 offset:35840
	ds_read_b128 v[208:211], v150 offset:36864
	ds_read_b128 v[212:215], v150 offset:37888
	ds_read_b128 v[216:219], v150 offset:38912
	ds_read_b128 v[220:223], v150 offset:39936
	global_load_lds_dwordx4 v[236:237], off
	v_lshl_add_u64 v[236:237], s[14:15], 0, v[128:129]
	s_add_i32 m0, s28, 0x16000
	s_add_u32 s14, s50, 0x40000
	s_addc_u32 s15, s51, 0
	global_load_lds_dwordx4 v[236:237], off
	v_lshl_add_u64 v[236:237], s[14:15], 0, v[134:135]
	s_mov_b32 m0, s31
	s_nop 0
	global_load_lds_dwordx4 v[236:237], off
	v_lshl_add_u64 v[236:237], s[14:15], 0, v[130:131]
	s_mov_b32 m0, s34
	s_nop 0
	global_load_lds_dwordx4 v[236:237], off
	s_waitcnt vmcnt(8)
	s_waitcnt lgkmcnt(0)
	s_setprio 1
	s_barrier
	v_mfma_f32_16x16x32_bf16 v[120:123], v[152:155], v[184:187], v[120:123]
	v_mfma_f32_16x16x32_bf16 v[112:115], v[160:163], v[184:187], v[112:115]
	v_mfma_f32_16x16x32_bf16 v[108:111], v[152:155], v[200:203], v[108:111]
	v_mfma_f32_16x16x32_bf16 v[96:99], v[160:163], v[200:203], v[96:99]
	v_mfma_f32_16x16x32_bf16 v[92:95], v[152:155], v[208:211], v[92:95]
	v_mfma_f32_16x16x32_bf16 v[80:83], v[160:163], v[208:211], v[80:83]
	v_mfma_f32_16x16x32_bf16 v[76:79], v[152:155], v[216:219], v[76:79]
	v_mfma_f32_16x16x32_bf16 v[64:67], v[160:163], v[216:219], v[64:67]
	v_mfma_f32_16x16x32_bf16 v[120:123], v[156:159], v[188:191], v[120:123]
	v_mfma_f32_16x16x32_bf16 v[112:115], v[164:167], v[188:191], v[112:115]
	v_mfma_f32_16x16x32_bf16 v[108:111], v[156:159], v[204:207], v[108:111]
	v_mfma_f32_16x16x32_bf16 v[96:99], v[164:167], v[204:207], v[96:99]
	v_mfma_f32_16x16x32_bf16 v[92:95], v[156:159], v[212:215], v[92:95]
	v_mfma_f32_16x16x32_bf16 v[80:83], v[164:167], v[212:215], v[80:83]
	v_mfma_f32_16x16x32_bf16 v[76:79], v[156:159], v[220:223], v[76:79]
	v_mfma_f32_16x16x32_bf16 v[64:67], v[164:167], v[220:223], v[64:67]
	v_mfma_f32_16x16x32_bf16 v[124:127], v[168:171], v[184:187], v[124:127]
	v_mfma_f32_16x16x32_bf16 v[116:119], v[176:179], v[184:187], v[116:119]
	v_mfma_f32_16x16x32_bf16 v[104:107], v[168:171], v[200:203], v[104:107]
	v_mfma_f32_16x16x32_bf16 v[100:103], v[176:179], v[200:203], v[100:103]
	v_mfma_f32_16x16x32_bf16 v[88:91], v[168:171], v[208:211], v[88:91]
	v_mfma_f32_16x16x32_bf16 v[84:87], v[176:179], v[208:211], v[84:87]
	v_mfma_f32_16x16x32_bf16 v[72:75], v[168:171], v[216:219], v[72:75]
	v_mfma_f32_16x16x32_bf16 v[68:71], v[176:179], v[216:219], v[68:71]
	v_mfma_f32_16x16x32_bf16 v[124:127], v[172:175], v[188:191], v[124:127]
	v_mfma_f32_16x16x32_bf16 v[116:119], v[180:183], v[188:191], v[116:119]
	v_mfma_f32_16x16x32_bf16 v[104:107], v[172:175], v[204:207], v[104:107]
	v_mfma_f32_16x16x32_bf16 v[100:103], v[180:183], v[204:207], v[100:103]
	v_mfma_f32_16x16x32_bf16 v[88:91], v[172:175], v[212:215], v[88:91]
	v_mfma_f32_16x16x32_bf16 v[84:87], v[180:183], v[212:215], v[84:87]
	v_mfma_f32_16x16x32_bf16 v[72:75], v[172:175], v[220:223], v[72:75]
	v_mfma_f32_16x16x32_bf16 v[68:71], v[180:183], v[220:223], v[68:71]
	s_barrier
; #define PG8_STAGE(bufoff, gbase, voff) do { _Pragma("unroll") for (int _i = 0; _i < 2; ++_i) \
;         __builtin_amdgcn_global_load_lds((const unsigned*)((const char*)(gbase) + (voff)[_i]), (PG8_LAS unsigned*)(lds + (bufoff) + ldsw + _i * 8192), 16, 0, 0); } while (0)
; #define PG8_LDA(dst, b, h) do { _Pragma("unroll") for (int m = 0; m < 4; ++m) _Pragma("unroll") for (int k = 0; k < 2; ++k) dst[m][k] = *(const PG8_LAS bf16x8*)(lds + PG8_SA(b, h) + aoff + m * 2048 + k * 1024); } while (0)
; #define PG8_MMA(ai, bj, At, Bt) do { __builtin_amdgcn_s_setprio(1); _Pragma("unroll") for (int m = 0; m < 4; ++m) _Pragma("unroll") for (int n = 0; n < 2; ++n) _Pragma("unroll") for (int k = 0; k < 2; ++k) \
;         acc[ai][bj][m][n] = __builtin_amdgcn_mfma_f32_16x16x32_bf16(Bt[n][k], At[m][k], acc[ai][bj][m][n], 0, 0, 0); __builtin_amdgcn_s_setprio(0); } while (0)
; #define PG8_WAIT_V(n) asm volatile("s_waitcnt vmcnt(" #n ")" ::: "memory")
; #define PG8_WAIT_L(n) asm volatile("s_waitcnt lgkmcnt(" #n ")" ::: "memory")
; #define PG8_BAR __builtin_amdgcn_s_barrier()
; #define PG8_SCHED __builtin_amdgcn_sched_barrier(0)
;     __device__ __forceinline__ void operator()(const f32x4 (&acc)[2][2][4][2], const Unit& u, int wr, int wc, int fr, int fq) const {
;     ...
;             for (int m = 0; m < 4; ++m) sv[ai][m] = ssq[row0 + ai * HALF + m * 16];
; template <class Epi, class Sched, bool ALIGN_EPI = false, bool SP2 = true>
; __device__ __forceinline__ void gemm_phase(PG8_LAS unsigned char* lds, const Gemm g, const Sched& S, const Epi& E) {
;     ...
;             PG8_LDA(At, 1, 1); PG8_STAGE(PG8_SB(1, 0), b3, voffB); PG8_STAGE(PG8_SB(1, 1), b3 + hstep, voffB); PG8_STAGE(PG8_SA(1, 0), a3, voffA);
;             PG8_WAIT_V(8); PG8_WAIT_L(0); PG8_BAR; PG8_MMA(1, 0, At, B0); PG8_MMA(1, 1, At, B1); PG8_BAR; PG8_SCHED;
	s_setprio 0
	s_add_i32 s14, s70, s28
	v_lshl_add_u64 v[148:149], v[148:149], 0, s[18:19]
	s_mov_b32 m0, s14
	ds_read_b128 v[184:187], v150 offset:49152
	ds_read_b128 v[188:191], v150 offset:50176
	ds_read_b128 v[200:203], v150 offset:51200
	ds_read_b128 v[204:207], v150 offset:52224
	ds_read_b128 v[208:211], v150 offset:53248
	ds_read_b128 v[212:215], v150 offset:54272
	ds_read_b128 v[216:219], v150 offset:55296
	ds_read_b128 v[220:223], v150 offset:56320
	global_load_lds_dwordx4 v[148:149], off
	s_add_i32 m0, s14, 0x2000
	v_lshl_add_u64 v[148:149], v[224:225], 0, s[18:19]
	global_load_lds_dwordx4 v[148:149], off
	v_lshl_add_u64 v[148:149], v[226:227], 0, s[18:19]
	s_mov_b32 m0, s52
	s_nop 0
	global_load_lds_dwordx4 v[148:149], off
	v_lshl_add_u64 v[148:149], v[234:235], 0, s[18:19]
	s_mov_b32 m0, s53
	s_nop 0
	global_load_lds_dwordx4 v[148:149], off
	s_waitcnt vmcnt(6)
	s_waitcnt lgkmcnt(0)
	s_cmp_lg_u32 s60, 12
	s_cbranch_scc1 .Lgu_no_ssq_prefetch
	v_lshl_add_u32 v148, s58, 8, v145
	v_ashrrev_i32_e32 v149, 31, v148
	v_lshl_add_u64 v[148:149], v[148:149], 3, s[10:11]
	global_load_dwordx2 v[238:239], v[148:149], off
	global_load_dwordx2 v[240:241], v[148:149], off offset:128
	global_load_dwordx2 v[242:243], v[148:149], off offset:256
	global_load_dwordx2 v[244:245], v[148:149], off offset:384
	global_load_dwordx2 v[246:247], v[148:149], off offset:1024
	global_load_dwordx2 v[248:249], v[148:149], off offset:1152
	global_load_dwordx2 v[250:251], v[148:149], off offset:1280
	global_load_dwordx2 v[228:229], v[148:149], off offset:1408
.Lgu_no_ssq_prefetch:
	s_setprio 1
	s_barrier
	v_mfma_f32_16x16x32_bf16 v[60:63], v[152:155], v[184:187], v[60:63]
	v_mfma_f32_16x16x32_bf16 v[48:51], v[160:163], v[184:187], v[48:51]
	v_mfma_f32_16x16x32_bf16 v[44:47], v[152:155], v[200:203], v[44:47]
	v_mfma_f32_16x16x32_bf16 v[32:35], v[160:163], v[200:203], v[32:35]
	v_mfma_f32_16x16x32_bf16 v[28:31], v[152:155], v[208:211], v[28:31]
	v_mfma_f32_16x16x32_bf16 v[16:19], v[160:163], v[208:211], v[16:19]
	v_mfma_f32_16x16x32_bf16 v[12:15], v[152:155], v[216:219], v[12:15]
	v_mfma_f32_16x16x32_bf16 v[4:7], v[160:163], v[216:219], v[4:7]
	v_mfma_f32_16x16x32_bf16 v[60:63], v[156:159], v[188:191], v[60:63]
	v_mfma_f32_16x16x32_bf16 v[48:51], v[164:167], v[188:191], v[48:51]
	v_mfma_f32_16x16x32_bf16 v[44:47], v[156:159], v[204:207], v[44:47]
	v_mfma_f32_16x16x32_bf16 v[32:35], v[164:167], v[204:207], v[32:35]
	v_mfma_f32_16x16x32_bf16 v[28:31], v[156:159], v[212:215], v[28:31]
	v_mfma_f32_16x16x32_bf16 v[16:19], v[164:167], v[212:215], v[16:19]
	v_mfma_f32_16x16x32_bf16 v[12:15], v[156:159], v[220:223], v[12:15]
	v_mfma_f32_16x16x32_bf16 v[4:7], v[164:167], v[220:223], v[4:7]
	v_mfma_f32_16x16x32_bf16 v[56:59], v[168:171], v[184:187], v[56:59]
	v_mfma_f32_16x16x32_bf16 v[52:55], v[176:179], v[184:187], v[52:55]
	v_mfma_f32_16x16x32_bf16 v[40:43], v[168:171], v[200:203], v[40:43]
	v_mfma_f32_16x16x32_bf16 v[36:39], v[176:179], v[200:203], v[36:39]
	v_mfma_f32_16x16x32_bf16 v[24:27], v[168:171], v[208:211], v[24:27]
	v_mfma_f32_16x16x32_bf16 v[20:23], v[176:179], v[208:211], v[20:23]
	v_mfma_f32_16x16x32_bf16 v[8:11], v[168:171], v[216:219], v[8:11]
	v_mfma_f32_16x16x32_bf16 v[0:3], v[176:179], v[216:219], v[0:3]
	v_mfma_f32_16x16x32_bf16 v[56:59], v[172:175], v[188:191], v[56:59]
	v_mfma_f32_16x16x32_bf16 v[52:55], v[180:183], v[188:191], v[52:55]
	v_mfma_f32_16x16x32_bf16 v[40:43], v[172:175], v[204:207], v[40:43]
	v_mfma_f32_16x16x32_bf16 v[36:39], v[180:183], v[204:207], v[36:39]
	v_mfma_f32_16x16x32_bf16 v[24:27], v[172:175], v[212:215], v[24:27]
	v_mfma_f32_16x16x32_bf16 v[20:23], v[180:183], v[212:215], v[20:23]
	v_mfma_f32_16x16x32_bf16 v[8:11], v[172:175], v[220:223], v[8:11]
	v_mfma_f32_16x16x32_bf16 v[0:3], v[180:183], v[220:223], v[0:3]
	s_barrier
	s_setprio 0
	s_add_i32 s60, s60, 2
	s_add_u32 s46, s46, 0x100
	s_addc_u32 s47, s47, 0
	s_add_u32 s6, s6, 0x100
	s_addc_u32 s7, s7, 0
	s_cmp_gt_u32 s60, 13
	s_cbranch_scc0 .LBB0_128
	s_and_b64 vcc, exec, s[20:21]
	s_cbranch_vccz .LBB0_131
	s_barrier
.LBB0_131:
	v_pk_mul_f32 v[126:127], v[122:123], v[126:127]
	v_pk_mul_f32 v[118:119], v[114:115], v[118:119]
	s_lshl_b32 s6, s16, 7
	s_or_b32 s6, s6, s35
	s_ashr_i32 s6, s6, 6
	s_mul_i32 s7, s58, 44
	s_add_i32 s6, s6, s7
	s_ashr_i32 s7, s6, 31
	s_lshl_b64 s[6:7], s[6:7], 15
	s_add_u32 s46, s62, s6
	s_addc_u32 s47, s63, s7
	v_pk_mul_f32 v[104:105], v[108:109], v[104:105]
	v_pk_mul_f32 v[106:107], v[110:111], v[106:107]
	v_pk_mul_f32 v[102:103], v[98:99], v[102:103]
	v_pk_mul_f32 v[88:89], v[92:93], v[88:89]
	v_pk_mul_f32 v[90:91], v[94:95], v[90:91]
	v_pk_mul_f32 v[86:87], v[82:83], v[86:87]
	v_pk_mul_f32 v[72:73], v[76:77], v[72:73]
	v_pk_mul_f32 v[74:75], v[78:79], v[74:75]
	v_pk_mul_f32 v[70:71], v[66:67], v[70:71]
	v_pk_mul_f32 v[56:57], v[60:61], v[56:57]
	v_pk_mul_f32 v[58:59], v[62:63], v[58:59]
	v_pk_mul_f32 v[54:55], v[50:51], v[54:55]
	v_pk_mul_f32 v[40:41], v[44:45], v[40:41]
	v_pk_mul_f32 v[42:43], v[46:47], v[42:43]
	v_pk_mul_f32 v[38:39], v[34:35], v[38:39]
	v_pk_mul_f32 v[24:25], v[28:29], v[24:25]
	v_pk_mul_f32 v[26:27], v[30:31], v[26:27]
	v_pk_mul_f32 v[22:23], v[18:19], v[22:23]
	v_pk_mul_f32 v[8:9], v[12:13], v[8:9]
	v_pk_mul_f32 v[10:11], v[14:15], v[10:11]
	v_pk_mul_f32 v[0:1], v[4:5], v[0:1]
	v_pk_mul_f32 v[2:3], v[6:7], v[2:3]
	s_waitcnt vmcnt(0)
; __device__ __forceinline__ unsigned cvt_pk_bf16(float lo, float hi) { unsigned r; asm volatile("v_cvt_pk_bf16_f32 %0, %1, %2" : "=v"(r) : "v"(lo), "v"(hi)); return r; }
; __device__ __forceinline__ float ssq_rs(ssq_t v) { return __builtin_amdgcn_rsqf((float)v * (1.0f / (16777216.0f * 1024.0f)) + RMS_EPS); }
;     __device__ __forceinline__ void operator()(const f32x4 (&acc)[2][2][4][2], const Unit& u, int wr, int wc, int fr, int fq) const {
;     ...
;             for (int m = 0; m < 4; ++m) sv[ai][m] = ssq[row0 + ai * HALF + m * 16];
; #pragma unroll
;         for (int ai = 0; ai < 2; ++ai)
; #pragma unroll
;             for (int m = 0; m < 4; ++m) rsv[ai][m] = ssq_rs(sv[ai][m]);
;         asm volatile("" ::: "memory");
; #pragma unroll
;         for (int ai = 0; ai < 2; ++ai)
; #pragma unroll
;             for (int m = 0; m < 4; ++m) {
;                 const int row = row0 + ai * HALF + m * 16;
;                 const float rs = rsv[ai][m], nrs = rs * -1.44269504089f, rs2 = rs * rs;
;                 typedef float f32x2 __attribute__((ext_vector_type(2)));
;                 float a[8];
; #pragma unroll
;                 for (int n = 0; n < 2; ++n)
; #pragma unroll
;                     for (int hf = 0; hf < 2; ++hf) {
;                         const f32x2 g2 = (f32x2){acc[ai][0][m][n][2 * hf], acc[ai][0][m][n][2 * hf + 1]}, u2 = (f32x2){acc[ai][1][m][n][2 * hf], acc[ai][1][m][n][2 * hf + 1]};
;                         const f32x2 t = g2 * nrs;
;                         f32x2 e; e.x = __builtin_amdgcn_exp2f(t.x); e.y = __builtin_amdgcn_exp2f(t.y);
;                         const f32x2 d = e + 1.0f;
;                         f32x2 r; r.x = __builtin_amdgcn_rcpf(d.x); r.y = __builtin_amdgcn_rcpf(d.y);
;                         const f32x2 o = (g2 * u2) * (r * rs2);
;                         a[n * 4 + 2 * hf] = o.x; a[n * 4 + 2 * hf + 1] = o.y;
;                     }
;                 u32x4 w; w.x = cvt_pk_bf16(a[0], a[1]); w.y = cvt_pk_bf16(a[2], a[3]); w.z = cvt_pk_bf16(a[4], a[5]); w.w = cvt_pk_bf16(a[6], a[7]);
;                 __builtin_nontemporal_store(w, (u32x4*)(O + ((size_t)(u.pm * (ldc >> 6) + (col0 >> 6)) * 256 + (row & 255)) * 64 + (col0 & 63)));
	v_mov_b32_e32 v152, v238
	v_mov_b32_e32 v153, v239
	v_mov_b32_e32 v154, v240
	v_mov_b32_e32 v155, v241
	v_mov_b32_e32 v158, v242
	v_mov_b32_e32 v159, v243
	v_mov_b32_e32 v160, v244
	v_mov_b32_e32 v161, v245
	v_mov_b32_e32 v162, v246
	v_mov_b32_e32 v163, v247
	v_mov_b32_e32 v164, v248
	v_mov_b32_e32 v165, v249
	v_mov_b32_e32 v166, v250
	v_mov_b32_e32 v167, v251
	v_mov_b32_e32 v148, v228
	v_mov_b32_e32 v149, v229
	v_ffbh_u32_e32 v141, v153
	v_min_u32_e32 v141, 32, v141
	v_lshlrev_b64 v[152:153], v141, v[152:153]
	v_min_u32_e32 v143, 1, v152
	v_or_b32_e32 v143, v153, v143
	v_cvt_f32_u32_e32 v143, v143
	v_sub_u32_e32 v141, 32, v141
	v_ldexp_f32 v141, v143, v141
	v_ffbh_u32_e32 v143, v155
	v_min_u32_e32 v143, 32, v143
	v_lshlrev_b64 v[152:153], v143, v[154:155]
	v_min_u32_e32 v144, 1, v152
	v_or_b32_e32 v144, v153, v144
	v_cvt_f32_u32_e32 v144, v144
	v_sub_u32_e32 v143, 32, v143
	v_fmamk_f32 v141, v141, 0x2e800000, v193
	v_rsq_f32_e32 v141, v141
	v_ldexp_f32 v143, v144, v143
	v_fmamk_f32 v143, v143, 0x2e800000, v193
	v_rsq_f32_e32 v156, v143
	v_ffbh_u32_e32 v143, v159
	v_min_u32_e32 v143, 32, v143
	v_lshlrev_b64 v[152:153], v143, v[158:159]
	v_min_u32_e32 v144, 1, v152
	v_or_b32_e32 v144, v153, v144
	v_cvt_f32_u32_e32 v144, v144
	v_sub_u32_e32 v143, 32, v143
	v_ldexp_f32 v143, v144, v143
	v_fmamk_f32 v143, v143, 0x2e800000, v193
	v_rsq_f32_e32 v155, v143
	v_ffbh_u32_e32 v143, v161
	v_min_u32_e32 v143, 32, v143
	v_lshlrev_b64 v[152:153], v143, v[160:161]
	v_min_u32_e32 v144, 1, v152
	v_or_b32_e32 v144, v153, v144
	v_cvt_f32_u32_e32 v144, v144
	v_sub_u32_e32 v143, 32, v143
	v_ldexp_f32 v143, v144, v143
	v_fmamk_f32 v143, v143, 0x2e800000, v193
	v_rsq_f32_e32 v154, v143
	v_ffbh_u32_e32 v143, v163
	v_min_u32_e32 v143, 32, v143
	v_lshlrev_b64 v[152:153], v143, v[162:163]
	v_min_u32_e32 v144, 1, v152
	v_or_b32_e32 v144, v153, v144
	v_cvt_f32_u32_e32 v144, v144
	v_sub_u32_e32 v143, 32, v143
	v_ldexp_f32 v143, v144, v143
	v_ffbh_u32_e32 v144, v165
	v_min_u32_e32 v144, 32, v144
	v_lshlrev_b64 v[152:153], v144, v[164:165]
	v_min_u32_e32 v146, 1, v152
	v_or_b32_e32 v146, v153, v146
	v_cvt_f32_u32_e32 v146, v146
	v_sub_u32_e32 v144, 32, v144
	v_fmamk_f32 v143, v143, 0x2e800000, v193
	v_rsq_f32_e32 v143, v143
	v_ldexp_f32 v144, v146, v144
	v_fmamk_f32 v144, v144, 0x2e800000, v193
	v_rsq_f32_e32 v153, v144
	v_ffbh_u32_e32 v144, v167
	v_min_u32_e32 v144, 32, v144
	v_lshlrev_b64 v[158:159], v144, v[166:167]
	v_min_u32_e32 v146, 1, v158
	v_or_b32_e32 v146, v159, v146
	v_cvt_f32_u32_e32 v146, v146
	v_sub_u32_e32 v144, 32, v144
	v_ldexp_f32 v144, v146, v144
	v_fmamk_f32 v144, v144, 0x2e800000, v193
	v_rsq_f32_e32 v152, v144
	v_ffbh_u32_e32 v144, v149
	v_min_u32_e32 v144, 32, v144
	v_lshlrev_b64 v[148:149], v144, v[148:149]
	v_min_u32_e32 v146, 1, v148
	v_or_b32_e32 v146, v149, v146
	v_cvt_f32_u32_e32 v146, v146
	v_sub_u32_e32 v144, 32, v144
	v_ldexp_f32 v144, v146, v144
	v_mul_f32_e32 v146, 0xbfb8aa3b, v141
	v_pk_mul_f32 v[148:149], v[120:121], v[146:147] op_sel_hi:[1,0]
	v_fmamk_f32 v144, v144, 0x2e800000, v193
	v_exp_f32_e32 v148, v148
	v_exp_f32_e32 v149, v149
	v_rsq_f32_e32 v151, v144
	v_mul_f32_e32 v144, v141, v141
	v_pk_mul_f32 v[120:121], v[120:121], v[124:125]
	v_pk_add_f32 v[148:149], v[148:149], 1.0 op_sel_hi:[1,0]
	v_pk_mul_f32 v[122:123], v[122:123], v[146:147] op_sel_hi:[1,0]
	v_rcp_f32_e32 v148, v148
	v_rcp_f32_e32 v149, v149
	v_pk_mul_f32 v[114:115], v[114:115], v[146:147] op_sel_hi:[1,0]
	v_exp_f32_e32 v122, v122
	v_exp_f32_e32 v123, v123
	v_pk_mul_f32 v[124:125], v[144:145], v[148:149] op_sel_hi:[0,1]
	v_pk_mul_f32 v[120:121], v[120:121], v[124:125]
	v_pk_mul_f32 v[124:125], v[112:113], v[146:147] op_sel_hi:[1,0]
	v_exp_f32_e32 v114, v114
	v_exp_f32_e32 v124, v124
	v_exp_f32_e32 v125, v125
	v_exp_f32_e32 v115, v115
	v_pk_add_f32 v[122:123], v[122:123], 1.0 op_sel_hi:[1,0]
	v_pk_mul_f32 v[112:113], v[112:113], v[116:117]
	v_pk_add_f32 v[124:125], v[124:125], 1.0 op_sel_hi:[1,0]
	v_pk_add_f32 v[114:115], v[114:115], 1.0 op_sel_hi:[1,0]
	v_rcp_f32_e32 v124, v124
	v_rcp_f32_e32 v125, v125
	v_rcp_f32_e32 v122, v122
	v_rcp_f32_e32 v123, v123
	v_rcp_f32_e32 v114, v114
	v_rcp_f32_e32 v115, v115
	v_pk_mul_f32 v[116:117], v[144:145], v[124:125] op_sel_hi:[0,1]
	v_pk_mul_f32 v[122:123], v[144:145], v[122:123] op_sel_hi:[0,1]
	v_pk_mul_f32 v[112:113], v[112:113], v[116:117]
	v_pk_mul_f32 v[114:115], v[144:145], v[114:115] op_sel_hi:[0,1]
	v_pk_mul_f32 v[122:123], v[126:127], v[122:123]
	v_pk_mul_f32 v[118:119], v[118:119], v[114:115]
	v_cvt_pk_bf16_f32 v114, v120, v121
	v_cvt_pk_bf16_f32 v115, v122, v123
	v_cvt_pk_bf16_f32 v116, v112, v113
	v_lshl_add_u64 v[112:113], s[46:47], 0, v[194:195]
	v_mov_b32_e32 v141, v195
	v_lshl_add_u64 v[112:113], v[112:113], 0, v[140:141]
	v_cvt_pk_bf16_f32 v117, v118, v119
	global_store_dwordx4 v[112:113], v[114:117], off nt
	s_nop 1
	v_mul_f32_e32 v114, 0xbfb8aa3b, v156
	v_pk_mul_f32 v[118:119], v[108:109], v[114:115] op_sel_hi:[1,0]
	v_mul_f32_e32 v116, v156, v156
	v_exp_f32_e32 v118, v118
	v_exp_f32_e32 v119, v119
	s_nop 0
	v_pk_add_f32 v[118:119], v[118:119], 1.0 op_sel_hi:[1,0]
	s_nop 0
	v_rcp_f32_e32 v118, v118
	v_rcp_f32_e32 v119, v119
	s_nop 0
	v_pk_mul_f32 v[108:109], v[116:117], v[118:119] op_sel_hi:[0,1]
	v_pk_mul_f32 v[104:105], v[104:105], v[108:109]
	v_pk_mul_f32 v[108:109], v[110:111], v[114:115] op_sel_hi:[1,0]
	s_nop 0
	v_exp_f32_e32 v108, v108
	v_exp_f32_e32 v109, v109
	s_nop 0
	v_pk_add_f32 v[108:109], v[108:109], 1.0 op_sel_hi:[1,0]
	s_nop 0
	v_rcp_f32_e32 v108, v108
	v_rcp_f32_e32 v109, v109
	s_nop 0
	v_pk_mul_f32 v[108:109], v[116:117], v[108:109] op_sel_hi:[0,1]
	v_pk_mul_f32 v[106:107], v[106:107], v[108:109]
; __device__ __forceinline__ unsigned cvt_pk_bf16(float lo, float hi) { unsigned r; asm volatile("v_cvt_pk_bf16_f32 %0, %1, %2" : "=v"(r) : "v"(lo), "v"(hi)); return r; }
;     __device__ __forceinline__ void operator()(const f32x4 (&acc)[2][2][4][2], const Unit& u, int wr, int wc, int fr, int fq) const {
;     ...
;         for (int ai = 0; ai < 2; ++ai)
; #pragma unroll
;             for (int m = 0; m < 4; ++m) {
;                 const int row = row0 + ai * HALF + m * 16;
;                 const float rs = rsv[ai][m], nrs = rs * -1.44269504089f, rs2 = rs * rs;
;                 typedef float f32x2 __attribute__((ext_vector_type(2)));
;                 float a[8];
; #pragma unroll
;                 for (int n = 0; n < 2; ++n)
; #pragma unroll
;                     for (int hf = 0; hf < 2; ++hf) {
;                         const f32x2 g2 = (f32x2){acc[ai][0][m][n][2 * hf], acc[ai][0][m][n][2 * hf + 1]}, u2 = (f32x2){acc[ai][1][m][n][2 * hf], acc[ai][1][m][n][2 * hf + 1]};
;                         const f32x2 t = g2 * nrs;
;                         f32x2 e; e.x = __builtin_amdgcn_exp2f(t.x); e.y = __builtin_amdgcn_exp2f(t.y);
;                         const f32x2 d = e + 1.0f;
;                         f32x2 r; r.x = __builtin_amdgcn_rcpf(d.x); r.y = __builtin_amdgcn_rcpf(d.y);
;                         const f32x2 o = (g2 * u2) * (r * rs2);
;                         a[n * 4 + 2 * hf] = o.x; a[n * 4 + 2 * hf + 1] = o.y;
;                     }
;                 u32x4 w; w.x = cvt_pk_bf16(a[0], a[1]); w.y = cvt_pk_bf16(a[2], a[3]); w.z = cvt_pk_bf16(a[4], a[5]); w.w = cvt_pk_bf16(a[6], a[7]);
;                 __builtin_nontemporal_store(w, (u32x4*)(O + ((size_t)(u.pm * (ldc >> 6) + (col0 >> 6)) * 256 + (row & 255)) * 64 + (col0 & 63)));
	v_pk_mul_f32 v[108:109], v[96:97], v[114:115] op_sel_hi:[1,0]
	v_pk_mul_f32 v[96:97], v[96:97], v[100:101]
	v_exp_f32_e32 v108, v108
	v_exp_f32_e32 v109, v109
	s_nop 0
	v_pk_add_f32 v[108:109], v[108:109], 1.0 op_sel_hi:[1,0]
	s_nop 0
	v_rcp_f32_e32 v108, v108
	v_rcp_f32_e32 v109, v109
	s_nop 0
	v_pk_mul_f32 v[100:101], v[116:117], v[108:109] op_sel_hi:[0,1]
	v_pk_mul_f32 v[100:101], v[96:97], v[100:101]
	v_pk_mul_f32 v[96:97], v[98:99], v[114:115] op_sel_hi:[1,0]
	s_nop 0
	v_exp_f32_e32 v96, v96
	v_exp_f32_e32 v97, v97
	s_nop 0
	v_pk_add_f32 v[96:97], v[96:97], 1.0 op_sel_hi:[1,0]
	s_nop 0
	v_rcp_f32_e32 v96, v96
	v_rcp_f32_e32 v97, v97
	s_nop 0
	v_pk_mul_f32 v[96:97], v[116:117], v[96:97] op_sel_hi:[0,1]
	v_pk_mul_f32 v[102:103], v[102:103], v[96:97]
	v_cvt_pk_bf16_f32 v96, v104, v105
	v_cvt_pk_bf16_f32 v97, v106, v107
	v_cvt_pk_bf16_f32 v98, v100, v101
	s_nop 0
	v_cvt_pk_bf16_f32 v99, v102, v103
	global_store_dwordx4 v[112:113], v[96:99], off offset:2048 nt
	s_nop 1
	v_mul_f32_e32 v96, 0xbfb8aa3b, v155
	v_pk_mul_f32 v[100:101], v[92:93], v[96:97] op_sel_hi:[1,0]
	v_mul_f32_e32 v98, v155, v155
	v_exp_f32_e32 v100, v100
	v_exp_f32_e32 v101, v101
	s_nop 0
	v_pk_add_f32 v[100:101], v[100:101], 1.0 op_sel_hi:[1,0]
	s_nop 0
	v_rcp_f32_e32 v100, v100
	v_rcp_f32_e32 v101, v101
	s_nop 0
	v_pk_mul_f32 v[92:93], v[98:99], v[100:101] op_sel_hi:[0,1]
	v_pk_mul_f32 v[88:89], v[88:89], v[92:93]
	v_pk_mul_f32 v[92:93], v[94:95], v[96:97] op_sel_hi:[1,0]
	s_nop 0
	v_exp_f32_e32 v92, v92
	v_exp_f32_e32 v93, v93
	s_nop 0
	v_pk_add_f32 v[92:93], v[92:93], 1.0 op_sel_hi:[1,0]
	s_nop 0
	v_rcp_f32_e32 v92, v92
	v_rcp_f32_e32 v93, v93
	s_nop 0
	v_pk_mul_f32 v[92:93], v[98:99], v[92:93] op_sel_hi:[0,1]
	v_pk_mul_f32 v[90:91], v[90:91], v[92:93]
	v_pk_mul_f32 v[92:93], v[80:81], v[96:97] op_sel_hi:[1,0]
	v_pk_mul_f32 v[80:81], v[80:81], v[84:85]
	v_exp_f32_e32 v92, v92
	v_exp_f32_e32 v93, v93
	s_nop 0
	v_pk_add_f32 v[92:93], v[92:93], 1.0 op_sel_hi:[1,0]
	s_nop 0
	v_rcp_f32_e32 v92, v92
	v_rcp_f32_e32 v93, v93
	s_nop 0
	v_pk_mul_f32 v[84:85], v[98:99], v[92:93] op_sel_hi:[0,1]
	v_pk_mul_f32 v[84:85], v[80:81], v[84:85]
	v_pk_mul_f32 v[80:81], v[82:83], v[96:97] op_sel_hi:[1,0]
	s_nop 0
	v_exp_f32_e32 v80, v80
	v_exp_f32_e32 v81, v81
	s_nop 0
	v_pk_add_f32 v[80:81], v[80:81], 1.0 op_sel_hi:[1,0]
	s_nop 0
	v_rcp_f32_e32 v80, v80
	v_rcp_f32_e32 v81, v81
	s_nop 0
	v_pk_mul_f32 v[80:81], v[98:99], v[80:81] op_sel_hi:[0,1]
	v_pk_mul_f32 v[86:87], v[86:87], v[80:81]
	v_cvt_pk_bf16_f32 v80, v88, v89
	v_cvt_pk_bf16_f32 v81, v90, v91
	v_cvt_pk_bf16_f32 v82, v84, v85
	v_add_co_u32_e32 v84, vcc, s23, v112
	v_cvt_pk_bf16_f32 v83, v86, v87
	s_nop 1
	v_addc_co_u32_e32 v85, vcc, 0, v113, vcc
	global_store_dwordx4 v[84:85], v[80:83], off nt
	s_nop 1
	v_mul_f32_e32 v80, 0xbfb8aa3b, v154
	v_pk_mul_f32 v[86:87], v[76:77], v[80:81] op_sel_hi:[1,0]
	v_mul_f32_e32 v82, v154, v154
	v_exp_f32_e32 v86, v86
	v_exp_f32_e32 v87, v87
	s_nop 0
	v_pk_add_f32 v[86:87], v[86:87], 1.0 op_sel_hi:[1,0]
	s_nop 0
	v_rcp_f32_e32 v86, v86
	v_rcp_f32_e32 v87, v87
	s_nop 0
	v_pk_mul_f32 v[76:77], v[82:83], v[86:87] op_sel_hi:[0,1]
	v_pk_mul_f32 v[72:73], v[72:73], v[76:77]
	v_pk_mul_f32 v[76:77], v[78:79], v[80:81] op_sel_hi:[1,0]
	s_nop 0
	v_exp_f32_e32 v76, v76
	v_exp_f32_e32 v77, v77
	s_nop 0
	v_pk_add_f32 v[76:77], v[76:77], 1.0 op_sel_hi:[1,0]
	s_nop 0
	v_rcp_f32_e32 v76, v76
	v_rcp_f32_e32 v77, v77
	s_nop 0
	v_pk_mul_f32 v[76:77], v[82:83], v[76:77] op_sel_hi:[0,1]
	v_pk_mul_f32 v[74:75], v[74:75], v[76:77]
	v_pk_mul_f32 v[76:77], v[64:65], v[80:81] op_sel_hi:[1,0]
	v_pk_mul_f32 v[64:65], v[64:65], v[68:69]
	v_exp_f32_e32 v76, v76
	v_exp_f32_e32 v77, v77
	s_nop 0
	v_pk_add_f32 v[76:77], v[76:77], 1.0 op_sel_hi:[1,0]
	s_nop 0
	v_rcp_f32_e32 v76, v76
	v_rcp_f32_e32 v77, v77
	s_nop 0
	v_pk_mul_f32 v[68:69], v[82:83], v[76:77] op_sel_hi:[0,1]
	v_pk_mul_f32 v[68:69], v[64:65], v[68:69]
	v_pk_mul_f32 v[64:65], v[66:67], v[80:81] op_sel_hi:[1,0]
	s_nop 0
	v_exp_f32_e32 v64, v64
	v_exp_f32_e32 v65, v65
	s_nop 0
	v_pk_add_f32 v[64:65], v[64:65], 1.0 op_sel_hi:[1,0]
	s_nop 0
	v_rcp_f32_e32 v64, v64
	v_rcp_f32_e32 v65, v65
	s_nop 0
	v_pk_mul_f32 v[64:65], v[82:83], v[64:65] op_sel_hi:[0,1]
	v_pk_mul_f32 v[70:71], v[70:71], v[64:65]
	v_cvt_pk_bf16_f32 v64, v72, v73
	v_cvt_pk_bf16_f32 v65, v74, v75
	v_cvt_pk_bf16_f32 v66, v68, v69
	s_nop 0
	v_cvt_pk_bf16_f32 v67, v70, v71
	global_store_dwordx4 v[84:85], v[64:67], off offset:2048 nt
	s_nop 1
	v_mul_f32_e32 v64, 0xbfb8aa3b, v143
	v_pk_mul_f32 v[68:69], v[60:61], v[64:65] op_sel_hi:[1,0]
	v_mul_f32_e32 v66, v143, v143
	v_exp_f32_e32 v68, v68
	v_exp_f32_e32 v69, v69
	v_pk_mul_f32 v[50:51], v[50:51], v[64:65] op_sel_hi:[1,0]
	v_mov_b32_e32 v143, v195
	v_exp_f32_e32 v50, v50
	v_pk_add_f32 v[68:69], v[68:69], 1.0 op_sel_hi:[1,0]
	v_exp_f32_e32 v51, v51
	v_rcp_f32_e32 v68, v68
	v_rcp_f32_e32 v69, v69
	v_pk_add_f32 v[50:51], v[50:51], 1.0 op_sel_hi:[1,0]
	s_nop 0
	v_rcp_f32_e32 v50, v50
	v_pk_mul_f32 v[60:61], v[66:67], v[68:69] op_sel_hi:[0,1]
	v_pk_mul_f32 v[56:57], v[56:57], v[60:61]
	v_pk_mul_f32 v[60:61], v[62:63], v[64:65] op_sel_hi:[1,0]
	v_rcp_f32_e32 v51, v51
	v_exp_f32_e32 v60, v60
	v_exp_f32_e32 v61, v61
	v_pk_mul_f32 v[50:51], v[66:67], v[50:51] op_sel_hi:[0,1]
	v_pk_mul_f32 v[54:55], v[54:55], v[50:51]
	v_pk_add_f32 v[60:61], v[60:61], 1.0 op_sel_hi:[1,0]
	v_cvt_pk_bf16_f32 v50, v56, v57
	s_nop 0
	v_rcp_f32_e32 v60, v60
	v_rcp_f32_e32 v61, v61
	s_nop 0
	v_pk_mul_f32 v[60:61], v[66:67], v[60:61] op_sel_hi:[0,1]
	v_pk_mul_f32 v[58:59], v[58:59], v[60:61]
	v_pk_mul_f32 v[60:61], v[48:49], v[64:65] op_sel_hi:[1,0]
	v_pk_mul_f32 v[48:49], v[48:49], v[52:53]
; #define PG8_BAR __builtin_amdgcn_s_barrier()
;     __device__ __forceinline__ void operator()(const f32x4 (&acc)[2][2][4][2], const Unit& u, int wr, int wc, int fr, int fq) const {
;     ...
;         for (int ai = 0; ai < 2; ++ai)
; #pragma unroll
;             for (int m = 0; m < 4; ++m) {
;                 const int row = row0 + ai * HALF + m * 16;
;                 const float rs = rsv[ai][m], nrs = rs * -1.44269504089f, rs2 = rs * rs;
;                 typedef float f32x2 __attribute__((ext_vector_type(2)));
;                 float a[8];
; #pragma unroll
;                 for (int n = 0; n < 2; ++n)
; #pragma unroll
;                     for (int hf = 0; hf < 2; ++hf) {
;                         const f32x2 g2 = (f32x2){acc[ai][0][m][n][2 * hf], acc[ai][0][m][n][2 * hf + 1]}, u2 = (f32x2){acc[ai][1][m][n][2 * hf], acc[ai][1][m][n][2 * hf + 1]};
;                         const f32x2 t = g2 * nrs;
;                         f32x2 e; e.x = __builtin_amdgcn_exp2f(t.x); e.y = __builtin_amdgcn_exp2f(t.y);
;                         const f32x2 d = e + 1.0f;
;                         f32x2 r; r.x = __builtin_amdgcn_rcpf(d.x); r.y = __builtin_amdgcn_rcpf(d.y);
;                         const f32x2 o = (g2 * u2) * (r * rs2);
;                         a[n * 4 + 2 * hf] = o.x; a[n * 4 + 2 * hf + 1] = o.y;
;                     }
;                 u32x4 w; w.x = cvt_pk_bf16(a[0], a[1]); w.y = cvt_pk_bf16(a[2], a[3]); w.z = cvt_pk_bf16(a[4], a[5]); w.w = cvt_pk_bf16(a[6], a[7]);
;                 __builtin_nontemporal_store(w, (u32x4*)(O + ((size_t)(u.pm * (ldc >> 6) + (col0 >> 6)) * 256 + (row & 255)) * 64 + (col0 & 63)));
; template <class Epi, class Sched, bool ALIGN_EPI = false, bool SP2 = true>
; __device__ __forceinline__ void gemm_phase(PG8_LAS unsigned char* lds, const Gemm g, const Sched& S, const Epi& E) {
;     ...
;         if constexpr (!Epi::AFTER_DRAIN) { E(acc, cur, wr, wc, fr, fq); S.done(cur); }
;         if (!has_next) break;
; #pragma unroll
;         for (int a = 0; a < 2; ++a)
; #pragma unroll
;             for (int b = 0; b < 2; ++b)
; #pragma unroll
;                 for (int m = 0; m < 4; ++m)
; #pragma unroll
;                     for (int n = 0; n < 2; ++n) acc[a][b][m][n] = (f32x4){0.f, 0.f, 0.f, 0.f};
;         cur = nxt; cA = nA; cB = nB; ++ui;
;         if constexpr (ALIGN_EPI) { if (wr == 1) PG8_BAR; }
	v_exp_f32_e32 v60, v60
	v_exp_f32_e32 v61, v61
	v_cvt_pk_bf16_f32 v51, v58, v59
	s_nop 0
	v_pk_add_f32 v[60:61], v[60:61], 1.0 op_sel_hi:[1,0]
	s_nop 0
	v_rcp_f32_e32 v60, v60
	v_rcp_f32_e32 v61, v61
	s_nop 0
	v_pk_mul_f32 v[52:53], v[66:67], v[60:61] op_sel_hi:[0,1]
	v_pk_mul_f32 v[48:49], v[48:49], v[52:53]
	s_nop 0
	v_cvt_pk_bf16_f32 v52, v48, v49
	v_lshl_add_u64 v[48:49], s[46:47], 0, v[142:143]
	v_lshl_add_u64 v[48:49], v[48:49], 0, v[140:141]
	v_cvt_pk_bf16_f32 v53, v54, v55
	global_store_dwordx4 v[48:49], v[50:53], off nt
	s_mov_b64 s[46:47], -1
	s_nop 0
	v_mul_f32_e32 v50, 0xbfb8aa3b, v153
	v_pk_mul_f32 v[54:55], v[44:45], v[50:51] op_sel_hi:[1,0]
	v_mul_f32_e32 v52, v153, v153
	v_exp_f32_e32 v54, v54
	v_exp_f32_e32 v55, v55
	s_nop 0
	v_pk_add_f32 v[54:55], v[54:55], 1.0 op_sel_hi:[1,0]
	s_nop 0
	v_rcp_f32_e32 v54, v54
	v_rcp_f32_e32 v55, v55
	s_nop 0
	v_pk_mul_f32 v[44:45], v[52:53], v[54:55] op_sel_hi:[0,1]
	v_pk_mul_f32 v[40:41], v[40:41], v[44:45]
	v_pk_mul_f32 v[44:45], v[46:47], v[50:51] op_sel_hi:[1,0]
	s_nop 0
	v_exp_f32_e32 v44, v44
	v_exp_f32_e32 v45, v45
	s_nop 0
	v_pk_add_f32 v[44:45], v[44:45], 1.0 op_sel_hi:[1,0]
	s_nop 0
	v_rcp_f32_e32 v44, v44
	v_rcp_f32_e32 v45, v45
	s_nop 0
	v_pk_mul_f32 v[44:45], v[52:53], v[44:45] op_sel_hi:[0,1]
	v_pk_mul_f32 v[42:43], v[42:43], v[44:45]
	v_pk_mul_f32 v[44:45], v[32:33], v[50:51] op_sel_hi:[1,0]
	v_pk_mul_f32 v[32:33], v[32:33], v[36:37]
	v_exp_f32_e32 v44, v44
	v_exp_f32_e32 v45, v45
	s_nop 0
	v_pk_add_f32 v[44:45], v[44:45], 1.0 op_sel_hi:[1,0]
	s_nop 0
	v_rcp_f32_e32 v44, v44
	v_rcp_f32_e32 v45, v45
	s_nop 0
	v_pk_mul_f32 v[36:37], v[52:53], v[44:45] op_sel_hi:[0,1]
	v_pk_mul_f32 v[36:37], v[32:33], v[36:37]
	v_pk_mul_f32 v[32:33], v[34:35], v[50:51] op_sel_hi:[1,0]
	s_nop 0
	v_exp_f32_e32 v32, v32
	v_exp_f32_e32 v33, v33
	s_nop 0
	v_pk_add_f32 v[32:33], v[32:33], 1.0 op_sel_hi:[1,0]
	s_nop 0
	v_rcp_f32_e32 v32, v32
	v_rcp_f32_e32 v33, v33
	s_nop 0
	v_pk_mul_f32 v[32:33], v[52:53], v[32:33] op_sel_hi:[0,1]
	v_pk_mul_f32 v[38:39], v[38:39], v[32:33]
	v_cvt_pk_bf16_f32 v32, v40, v41
	v_cvt_pk_bf16_f32 v33, v42, v43
	v_cvt_pk_bf16_f32 v34, v36, v37
	s_nop 0
	v_cvt_pk_bf16_f32 v35, v38, v39
	global_store_dwordx4 v[48:49], v[32:35], off offset:2048 nt
	s_nop 1
	v_mul_f32_e32 v32, 0xbfb8aa3b, v152
	v_pk_mul_f32 v[36:37], v[28:29], v[32:33] op_sel_hi:[1,0]
	v_mul_f32_e32 v34, v152, v152
	v_exp_f32_e32 v36, v36
	v_exp_f32_e32 v37, v37
	s_nop 0
	v_pk_add_f32 v[36:37], v[36:37], 1.0 op_sel_hi:[1,0]
	s_nop 0
	v_rcp_f32_e32 v36, v36
	v_rcp_f32_e32 v37, v37
	s_nop 0
	v_pk_mul_f32 v[28:29], v[34:35], v[36:37] op_sel_hi:[0,1]
	v_pk_mul_f32 v[24:25], v[24:25], v[28:29]
	v_pk_mul_f32 v[28:29], v[30:31], v[32:33] op_sel_hi:[1,0]
	s_nop 0
	v_exp_f32_e32 v28, v28
	v_exp_f32_e32 v29, v29
	s_nop 0
	v_pk_add_f32 v[28:29], v[28:29], 1.0 op_sel_hi:[1,0]
	s_nop 0
	v_rcp_f32_e32 v28, v28
	v_rcp_f32_e32 v29, v29
	s_nop 0
	v_pk_mul_f32 v[28:29], v[34:35], v[28:29] op_sel_hi:[0,1]
	v_pk_mul_f32 v[26:27], v[26:27], v[28:29]
	v_pk_mul_f32 v[28:29], v[16:17], v[32:33] op_sel_hi:[1,0]
	v_pk_mul_f32 v[16:17], v[16:17], v[20:21]
	v_exp_f32_e32 v28, v28
	v_exp_f32_e32 v29, v29
	s_nop 0
	v_pk_add_f32 v[28:29], v[28:29], 1.0 op_sel_hi:[1,0]
	s_nop 0
	v_rcp_f32_e32 v28, v28
	v_rcp_f32_e32 v29, v29
	s_nop 0
	v_pk_mul_f32 v[20:21], v[34:35], v[28:29] op_sel_hi:[0,1]
	v_pk_mul_f32 v[20:21], v[16:17], v[20:21]
	v_pk_mul_f32 v[16:17], v[18:19], v[32:33] op_sel_hi:[1,0]
	s_nop 0
	v_exp_f32_e32 v16, v16
	v_exp_f32_e32 v17, v17
	s_nop 0
	v_pk_add_f32 v[16:17], v[16:17], 1.0 op_sel_hi:[1,0]
	s_nop 0
	v_rcp_f32_e32 v16, v16
	v_rcp_f32_e32 v17, v17
	s_nop 0
	v_pk_mul_f32 v[16:17], v[34:35], v[16:17] op_sel_hi:[0,1]
	v_pk_mul_f32 v[22:23], v[22:23], v[16:17]
	v_cvt_pk_bf16_f32 v16, v24, v25
	v_cvt_pk_bf16_f32 v17, v26, v27
	v_cvt_pk_bf16_f32 v18, v20, v21
	v_add_co_u32_e32 v20, vcc, s23, v48
	v_cvt_pk_bf16_f32 v19, v22, v23
	s_nop 1
	v_addc_co_u32_e32 v21, vcc, 0, v49, vcc
	global_store_dwordx4 v[20:21], v[16:19], off nt
	s_andn2_b64 vcc, exec, s[36:37]
	s_nop 0
	v_mul_f32_e32 v16, 0xbfb8aa3b, v151
	v_pk_mul_f32 v[22:23], v[12:13], v[16:17] op_sel_hi:[1,0]
	v_mul_f32_e32 v18, v151, v151
	v_exp_f32_e32 v22, v22
	v_exp_f32_e32 v23, v23
	s_nop 0
	v_pk_add_f32 v[22:23], v[22:23], 1.0 op_sel_hi:[1,0]
	s_nop 0
	v_rcp_f32_e32 v22, v22
	v_rcp_f32_e32 v23, v23
	s_nop 0
	v_pk_mul_f32 v[12:13], v[18:19], v[22:23] op_sel_hi:[0,1]
	v_pk_mul_f32 v[8:9], v[8:9], v[12:13]
	v_pk_mul_f32 v[12:13], v[14:15], v[16:17] op_sel_hi:[1,0]
	s_nop 0
	v_exp_f32_e32 v12, v12
	v_exp_f32_e32 v13, v13
	s_nop 0
	v_pk_add_f32 v[12:13], v[12:13], 1.0 op_sel_hi:[1,0]
	s_nop 0
	v_rcp_f32_e32 v12, v12
	v_rcp_f32_e32 v13, v13
	s_nop 0
	v_pk_mul_f32 v[12:13], v[18:19], v[12:13] op_sel_hi:[0,1]
	v_pk_mul_f32 v[10:11], v[10:11], v[12:13]
	v_pk_mul_f32 v[12:13], v[4:5], v[16:17] op_sel_hi:[1,0]
	s_nop 0
	v_exp_f32_e32 v12, v12
	v_exp_f32_e32 v13, v13
	s_nop 0
	v_pk_add_f32 v[12:13], v[12:13], 1.0 op_sel_hi:[1,0]
	s_nop 0
	v_rcp_f32_e32 v12, v12
	v_rcp_f32_e32 v13, v13
	s_nop 0
	v_pk_mul_f32 v[4:5], v[18:19], v[12:13] op_sel_hi:[0,1]
	v_pk_mul_f32 v[4:5], v[0:1], v[4:5]
	v_pk_mul_f32 v[0:1], v[6:7], v[16:17] op_sel_hi:[1,0]
	s_nop 0
	v_exp_f32_e32 v0, v0
	v_exp_f32_e32 v1, v1
	s_nop 0
	v_pk_add_f32 v[0:1], v[0:1], 1.0 op_sel_hi:[1,0]
	s_nop 0
	v_rcp_f32_e32 v0, v0
	v_rcp_f32_e32 v1, v1
	s_nop 0
	v_pk_mul_f32 v[0:1], v[18:19], v[0:1] op_sel_hi:[0,1]
	v_pk_mul_f32 v[6:7], v[2:3], v[0:1]
	v_cvt_pk_bf16_f32 v0, v8, v9
	v_cvt_pk_bf16_f32 v1, v10, v11
	v_cvt_pk_bf16_f32 v2, v4, v5
	s_nop 0
	v_cvt_pk_bf16_f32 v3, v6, v7
	global_store_dwordx4 v[20:21], v[0:3], off offset:2048 nt
	s_cbranch_vccnz .LBB0_124
	s_andn2_b64 vcc, exec, s[0:1]
	s_cbranch_vccnz .LBB0_123
	s_barrier
	s_branch .LBB0_123

; #define PG8_STAGE(bufoff, gbase, voff) do { _Pragma("unroll") for (int _i = 0; _i < 2; ++_i) \
;         __builtin_amdgcn_global_load_lds((const unsigned*)((const char*)(gbase) + (voff)[_i]), (PG8_LAS unsigned*)(lds + (bufoff) + ldsw + _i * 8192), 16, 0, 0); } while (0)
; #define PG8_LDA(dst, b, h) do { _Pragma("unroll") for (int m = 0; m < 4; ++m) _Pragma("unroll") for (int k = 0; k < 2; ++k) dst[m][k] = *(const PG8_LAS bf16x8*)(lds + PG8_SA(b, h) + aoff + m * 2048 + k * 1024); } while (0)
; #define PG8_LDB(dst, b, h) do { _Pragma("unroll") for (int n = 0; n < 2; ++n) _Pragma("unroll") for (int k = 0; k < 2; ++k) dst[n][k] = *(const PG8_LAS bf16x8*)(lds + PG8_SB(b, h) + boff + n * 2048 + k * 1024); } while (0)
; #define PG8_MMA(ai, bj, At, Bt) do { __builtin_amdgcn_s_setprio(1); _Pragma("unroll") for (int m = 0; m < 4; ++m) _Pragma("unroll") for (int n = 0; n < 2; ++n) _Pragma("unroll") for (int k = 0; k < 2; ++k) \
;         acc[ai][bj][m][n] = __builtin_amdgcn_mfma_f32_16x16x32_bf16(Bt[n][k], At[m][k], acc[ai][bj][m][n], 0, 0, 0); __builtin_amdgcn_s_setprio(0); } while (0)
; #define PG8_WAIT_V(n) asm volatile("s_waitcnt vmcnt(" #n ")" ::: "memory")
; #define PG8_WAIT_L(n) asm volatile("s_waitcnt lgkmcnt(" #n ")" ::: "memory")
; template <class Epi, class Sched, bool ALIGN_EPI = false, bool SP2 = true>
; __device__ __forceinline__ void gemm_phase(PG8_LAS unsigned char* lds, const Gemm g, const Sched& S, const Epi& E) {
;     ...
;             const bool last = (t == nt - 2);
;             const char* a1 = cA + (size_t)(t + 1) * kstepA;
;             const char* a2 = last ? nA : cA + (size_t)(t + 2) * kstepA; const char* b2 = last ? nB : cB + (size_t)(t + 2) * kstep;
;             const char* a3 = a2 + kstepA; const char* b3 = b2 + kstep;
;             if (last && has_next) S.a_ready(nxt);
;             if constexpr (SP2) {
;             PG8_LDB(B0, 0, 0); PG8_LDB(B1, 0, 1); PG8_SCHED; PG8_LDA(At, 0, 0); PG8_STAGE(PG8_SA(1, 1), a1 + hstepA, voffA);
;             PG8_WAIT_V(8); PG8_WAIT_L(0); PG8_BAR; PG8_MMA(0, 0, At, B0); PG8_MMA(0, 1, At, B1); PG8_BAR; PG8_SCHED;
;             PG8_LDA(At, 0, 1); PG8_STAGE(PG8_SB(0, 0), b2, voffB); PG8_STAGE(PG8_SB(0, 1), b2 + hstep, voffB); PG8_STAGE(PG8_SA(0, 0), a2, voffA);
;             PG8_WAIT_V(8); PG8_WAIT_L(0); PG8_BAR; PG8_MMA(1, 0, At, B0); PG8_MMA(1, 1, At, B1); PG8_BAR; PG8_SCHED;
.LBB0_236:
	s_add_u32 s14, s42, 0x4000
	s_addc_u32 s15, s43, 0
	s_cmp_eq_u32 s7, 40
	s_cselect_b32 s84, s10, s14
	s_cselect_b32 s85, s11, s15
	s_cselect_b32 vcc_lo, s52, s17
	s_cselect_b32 vcc_hi, s53, s6
	s_add_u32 s46, s84, 0x8000
	s_addc_u32 s47, s85, 0
	s_add_i32 s14, 0, 0x10000
	s_add_i32 s4, 0, 0x14000
	v_add_u32_e32 v140, s14, v235
	v_add_u32_e32 v156, s4, v235
	ds_read_b128 v[128:131], v140
	ds_read_b128 v[132:135], v140 offset:1024
	ds_read_b128 v[136:139], v140 offset:2048
	ds_read_b128 v[140:143], v140 offset:3072
	ds_read_b128 v[144:147], v156
	ds_read_b128 v[148:151], v156 offset:1024
	ds_read_b128 v[152:155], v156 offset:2048
	ds_read_b128 v[156:159], v156 offset:3072
	v_lshl_add_u64 v[212:213], s[42:43], 0, v[208:209]
	s_add_i32 m0, s59, 0xc000
	ds_read_b128 v[160:163], v237
	ds_read_b128 v[164:167], v237 offset:1024
	ds_read_b128 v[168:171], v237 offset:2048
	ds_read_b128 v[172:175], v237 offset:3072
	ds_read_b128 v[176:179], v237 offset:4096
	ds_read_b128 v[180:183], v237 offset:5120
	ds_read_b128 v[184:187], v237 offset:6144
	ds_read_b128 v[188:191], v237 offset:7168
	global_load_lds_dwordx4 v[212:213], off
	v_lshl_add_u64 v[212:213], s[42:43], 0, v[210:211]
	s_add_i32 m0, s59, 0xe000
	s_nop 0
	global_load_lds_dwordx4 v[212:213], off
	s_waitcnt vmcnt(8)
	s_waitcnt lgkmcnt(0)
	s_setprio 1
	s_barrier
	v_mfma_f32_16x16x32_bf16 v[124:127], v[128:131], v[160:163], v[124:127]
	v_mfma_f32_16x16x32_bf16 v[120:123], v[136:139], v[160:163], v[120:123]
	v_mfma_f32_16x16x32_bf16 v[108:111], v[128:131], v[168:171], v[108:111]
	v_mfma_f32_16x16x32_bf16 v[104:107], v[136:139], v[168:171], v[104:107]
	v_mfma_f32_16x16x32_bf16 v[92:95], v[128:131], v[176:179], v[92:95]
	v_mfma_f32_16x16x32_bf16 v[88:91], v[136:139], v[176:179], v[88:91]
	v_mfma_f32_16x16x32_bf16 v[76:79], v[128:131], v[184:187], v[76:79]
	v_mfma_f32_16x16x32_bf16 v[72:75], v[136:139], v[184:187], v[72:75]
	v_mfma_f32_16x16x32_bf16 v[124:127], v[132:135], v[164:167], v[124:127]
	v_mfma_f32_16x16x32_bf16 v[120:123], v[140:143], v[164:167], v[120:123]
	v_mfma_f32_16x16x32_bf16 v[108:111], v[132:135], v[172:175], v[108:111]
	v_mfma_f32_16x16x32_bf16 v[104:107], v[140:143], v[172:175], v[104:107]
	v_mfma_f32_16x16x32_bf16 v[92:95], v[132:135], v[180:183], v[92:95]
	v_mfma_f32_16x16x32_bf16 v[88:91], v[140:143], v[180:183], v[88:91]
	v_mfma_f32_16x16x32_bf16 v[76:79], v[132:135], v[188:191], v[76:79]
	v_mfma_f32_16x16x32_bf16 v[72:75], v[140:143], v[188:191], v[72:75]
	v_mfma_f32_16x16x32_bf16 v[116:119], v[144:147], v[160:163], v[116:119]
	v_mfma_f32_16x16x32_bf16 v[112:115], v[152:155], v[160:163], v[112:115]
	v_mfma_f32_16x16x32_bf16 v[100:103], v[144:147], v[168:171], v[100:103]
	v_mfma_f32_16x16x32_bf16 v[96:99], v[152:155], v[168:171], v[96:99]
	v_mfma_f32_16x16x32_bf16 v[84:87], v[144:147], v[176:179], v[84:87]
	v_mfma_f32_16x16x32_bf16 v[80:83], v[152:155], v[176:179], v[80:83]
	v_mfma_f32_16x16x32_bf16 v[68:71], v[144:147], v[184:187], v[68:71]
	v_mfma_f32_16x16x32_bf16 v[64:67], v[152:155], v[184:187], v[64:67]
	v_mfma_f32_16x16x32_bf16 v[116:119], v[148:151], v[164:167], v[116:119]
	v_mfma_f32_16x16x32_bf16 v[112:115], v[156:159], v[164:167], v[112:115]
	v_mfma_f32_16x16x32_bf16 v[100:103], v[148:151], v[172:175], v[100:103]
	v_mfma_f32_16x16x32_bf16 v[96:99], v[156:159], v[172:175], v[96:99]
	v_mfma_f32_16x16x32_bf16 v[84:87], v[148:151], v[180:183], v[84:87]
	v_mfma_f32_16x16x32_bf16 v[80:83], v[156:159], v[180:183], v[80:83]
	v_mfma_f32_16x16x32_bf16 v[68:71], v[148:151], v[188:191], v[68:71]
	v_mfma_f32_16x16x32_bf16 v[64:67], v[156:159], v[188:191], v[64:67]
	s_barrier
	s_setprio 0
	s_add_i32 s5, s14, s57
	v_lshl_add_u64 v[212:213], vcc, 0, v[194:195]
	s_mov_b32 m0, s5
	ds_read_b128 v[160:163], v237 offset:16384
	ds_read_b128 v[164:167], v237 offset:17408
	ds_read_b128 v[168:171], v237 offset:18432
	ds_read_b128 v[172:175], v237 offset:19456
	ds_read_b128 v[176:179], v237 offset:20480
	ds_read_b128 v[180:183], v237 offset:21504
	ds_read_b128 v[184:187], v237 offset:22528
	ds_read_b128 v[188:191], v237 offset:23552
	global_load_lds_dwordx4 v[212:213], off
	s_add_i32 m0, s5, 0x2000
	s_add_u32 s14, vcc_lo, 0xb0000
	v_lshl_add_u64 v[214:215], vcc, 0, v[204:205]
	s_addc_u32 s15, vcc_hi, 0
	s_add_i32 s4, s4, s57
	global_load_lds_dwordx4 v[214:215], off
	v_lshl_add_u64 v[216:217], s[14:15], 0, v[194:195]
	s_mov_b32 m0, s4
	s_nop 0
	global_load_lds_dwordx4 v[216:217], off
	v_lshl_add_u64 v[216:217], s[14:15], 0, v[204:205]
	s_add_i32 m0, s4, 0x2000
	s_nop 0
	global_load_lds_dwordx4 v[216:217], off
	v_lshl_add_u64 v[216:217], s[84:85], 0, v[200:201]
	s_mov_b32 m0, s59
	s_nop 0
	global_load_lds_dwordx4 v[216:217], off
	v_lshl_add_u64 v[216:217], s[84:85], 0, v[202:203]
	s_mov_b32 m0, s60
	s_nop 0
	global_load_lds_dwordx4 v[216:217], off
	s_waitcnt vmcnt(8)
	s_waitcnt lgkmcnt(0)
	s_setprio 1
	s_barrier
; #define PG8_STAGE(bufoff, gbase, voff) do { _Pragma("unroll") for (int _i = 0; _i < 2; ++_i) \
;         __builtin_amdgcn_global_load_lds((const unsigned*)((const char*)(gbase) + (voff)[_i]), (PG8_LAS unsigned*)(lds + (bufoff) + ldsw + _i * 8192), 16, 0, 0); } while (0)
; #define PG8_LDA(dst, b, h) do { _Pragma("unroll") for (int m = 0; m < 4; ++m) _Pragma("unroll") for (int k = 0; k < 2; ++k) dst[m][k] = *(const PG8_LAS bf16x8*)(lds + PG8_SA(b, h) + aoff + m * 2048 + k * 1024); } while (0)
; #define PG8_LDB(dst, b, h) do { _Pragma("unroll") for (int n = 0; n < 2; ++n) _Pragma("unroll") for (int k = 0; k < 2; ++k) dst[n][k] = *(const PG8_LAS bf16x8*)(lds + PG8_SB(b, h) + boff + n * 2048 + k * 1024); } while (0)
; #define PG8_MMA(ai, bj, At, Bt) do { __builtin_amdgcn_s_setprio(1); _Pragma("unroll") for (int m = 0; m < 4; ++m) _Pragma("unroll") for (int n = 0; n < 2; ++n) _Pragma("unroll") for (int k = 0; k < 2; ++k) \
;         acc[ai][bj][m][n] = __builtin_amdgcn_mfma_f32_16x16x32_bf16(Bt[n][k], At[m][k], acc[ai][bj][m][n], 0, 0, 0); __builtin_amdgcn_s_setprio(0); } while (0)
; #define PG8_WAIT_V(n) asm volatile("s_waitcnt vmcnt(" #n ")" ::: "memory")
; #define PG8_WAIT_L(n) asm volatile("s_waitcnt lgkmcnt(" #n ")" ::: "memory")
; #define PG8_BAR __builtin_amdgcn_s_barrier()
; #define PG8_SCHED __builtin_amdgcn_sched_barrier(0)
; template <class Epi, class Sched, bool ALIGN_EPI = false, bool SP2 = true>
; __device__ __forceinline__ void gemm_phase(PG8_LAS unsigned char* lds, const Gemm g, const Sched& S, const Epi& E) {
;     ...
;             PG8_WAIT_V(8); PG8_WAIT_L(0); PG8_BAR; PG8_MMA(1, 0, At, B0); PG8_MMA(1, 1, At, B1); PG8_BAR; PG8_SCHED;
;             PG8_LDB(B0, 1, 0); PG8_LDB(B1, 1, 1); PG8_SCHED; PG8_LDA(At, 1, 0); PG8_STAGE(PG8_SA(0, 1), a2 + hstepA, voffA);
;             PG8_WAIT_V(8); PG8_WAIT_L(0); PG8_BAR; PG8_MMA(0, 0, At, B0); PG8_MMA(0, 1, At, B1); PG8_BAR; PG8_SCHED;
;             PG8_LDA(At, 1, 1); PG8_STAGE(PG8_SB(1, 0), b3, voffB); PG8_STAGE(PG8_SB(1, 1), b3 + hstep, voffB); PG8_STAGE(PG8_SA(1, 0), a3, voffA);
;             PG8_WAIT_V(8); PG8_WAIT_L(0); PG8_BAR; PG8_MMA(1, 0, At, B0); PG8_MMA(1, 1, At, B1); PG8_BAR; PG8_SCHED;
	v_mfma_f32_16x16x32_bf16 v[60:63], v[128:131], v[160:163], v[60:63]
	v_mfma_f32_16x16x32_bf16 v[56:59], v[136:139], v[160:163], v[56:59]
	v_mfma_f32_16x16x32_bf16 v[44:47], v[128:131], v[168:171], v[44:47]
	v_mfma_f32_16x16x32_bf16 v[40:43], v[136:139], v[168:171], v[40:43]
	v_mfma_f32_16x16x32_bf16 v[28:31], v[128:131], v[176:179], v[28:31]
	v_mfma_f32_16x16x32_bf16 v[24:27], v[136:139], v[176:179], v[24:27]
	v_mfma_f32_16x16x32_bf16 v[12:15], v[128:131], v[184:187], v[12:15]
	v_mfma_f32_16x16x32_bf16 v[8:11], v[136:139], v[184:187], v[8:11]
	v_mfma_f32_16x16x32_bf16 v[60:63], v[132:135], v[164:167], v[60:63]
	v_mfma_f32_16x16x32_bf16 v[56:59], v[140:143], v[164:167], v[56:59]
	v_mfma_f32_16x16x32_bf16 v[44:47], v[132:135], v[172:175], v[44:47]
	v_mfma_f32_16x16x32_bf16 v[40:43], v[140:143], v[172:175], v[40:43]
	v_mfma_f32_16x16x32_bf16 v[28:31], v[132:135], v[180:183], v[28:31]
	v_mfma_f32_16x16x32_bf16 v[24:27], v[140:143], v[180:183], v[24:27]
	v_mfma_f32_16x16x32_bf16 v[12:15], v[132:135], v[188:191], v[12:15]
	v_mfma_f32_16x16x32_bf16 v[8:11], v[140:143], v[188:191], v[8:11]
	v_mfma_f32_16x16x32_bf16 v[52:55], v[144:147], v[160:163], v[52:55]
	v_mfma_f32_16x16x32_bf16 v[48:51], v[152:155], v[160:163], v[48:51]
	v_mfma_f32_16x16x32_bf16 v[36:39], v[144:147], v[168:171], v[36:39]
	v_mfma_f32_16x16x32_bf16 v[32:35], v[152:155], v[168:171], v[32:35]
	v_mfma_f32_16x16x32_bf16 v[20:23], v[144:147], v[176:179], v[20:23]
	v_mfma_f32_16x16x32_bf16 v[16:19], v[152:155], v[176:179], v[16:19]
	v_mfma_f32_16x16x32_bf16 v[4:7], v[144:147], v[184:187], v[4:7]
	v_mfma_f32_16x16x32_bf16 v[0:3], v[152:155], v[184:187], v[0:3]
	v_mfma_f32_16x16x32_bf16 v[52:55], v[148:151], v[164:167], v[52:55]
	v_mfma_f32_16x16x32_bf16 v[48:51], v[156:159], v[164:167], v[48:51]
	v_mfma_f32_16x16x32_bf16 v[36:39], v[148:151], v[172:175], v[36:39]
	v_mfma_f32_16x16x32_bf16 v[32:35], v[156:159], v[172:175], v[32:35]
	v_mfma_f32_16x16x32_bf16 v[20:23], v[148:151], v[180:183], v[20:23]
	v_mfma_f32_16x16x32_bf16 v[16:19], v[156:159], v[180:183], v[16:19]
	v_mfma_f32_16x16x32_bf16 v[4:7], v[148:151], v[188:191], v[4:7]
	v_mfma_f32_16x16x32_bf16 v[0:3], v[156:159], v[188:191], v[0:3]
	s_barrier
	s_setprio 0
	s_add_i32 s4, 0, 0x18000
	s_add_i32 s5, 0, 0x1c000
	v_add_u32_e32 v140, s4, v235
	v_add_u32_e32 v156, s5, v235
	ds_read_b128 v[128:131], v140
	ds_read_b128 v[132:135], v140 offset:1024
	ds_read_b128 v[136:139], v140 offset:2048
	ds_read_b128 v[140:143], v140 offset:3072
	ds_read_b128 v[144:147], v156
	ds_read_b128 v[148:151], v156 offset:1024
	ds_read_b128 v[152:155], v156 offset:2048
	ds_read_b128 v[156:159], v156 offset:3072
	s_add_u32 s14, s84, 0x4000
	s_addc_u32 s15, s85, 0
	s_mov_b32 m0, s70
	v_lshl_add_u64 v[216:217], s[14:15], 0, v[200:201]
	ds_read_b128 v[160:163], v237 offset:32768
	ds_read_b128 v[164:167], v237 offset:33792
	ds_read_b128 v[168:171], v237 offset:34816
	ds_read_b128 v[172:175], v237 offset:35840
	ds_read_b128 v[176:179], v237 offset:36864
	ds_read_b128 v[180:183], v237 offset:37888
	ds_read_b128 v[184:187], v237 offset:38912
	ds_read_b128 v[188:191], v237 offset:39936
	global_load_lds_dwordx4 v[216:217], off
	v_lshl_add_u64 v[216:217], s[14:15], 0, v[202:203]
	s_mov_b32 m0, s71
	s_nop 0
	global_load_lds_dwordx4 v[216:217], off
	s_waitcnt vmcnt(8)
	s_waitcnt lgkmcnt(0)
	s_setprio 1
	s_barrier
	v_mfma_f32_16x16x32_bf16 v[124:127], v[128:131], v[160:163], v[124:127]
	v_mfma_f32_16x16x32_bf16 v[120:123], v[136:139], v[160:163], v[120:123]
	v_mfma_f32_16x16x32_bf16 v[108:111], v[128:131], v[168:171], v[108:111]
	v_mfma_f32_16x16x32_bf16 v[104:107], v[136:139], v[168:171], v[104:107]
	v_mfma_f32_16x16x32_bf16 v[92:95], v[128:131], v[176:179], v[92:95]
	v_mfma_f32_16x16x32_bf16 v[88:91], v[136:139], v[176:179], v[88:91]
	v_mfma_f32_16x16x32_bf16 v[76:79], v[128:131], v[184:187], v[76:79]
	v_mfma_f32_16x16x32_bf16 v[72:75], v[136:139], v[184:187], v[72:75]
	v_mfma_f32_16x16x32_bf16 v[124:127], v[132:135], v[164:167], v[124:127]
	v_mfma_f32_16x16x32_bf16 v[120:123], v[140:143], v[164:167], v[120:123]
	v_mfma_f32_16x16x32_bf16 v[108:111], v[132:135], v[172:175], v[108:111]
	v_mfma_f32_16x16x32_bf16 v[104:107], v[140:143], v[172:175], v[104:107]
	v_mfma_f32_16x16x32_bf16 v[92:95], v[132:135], v[180:183], v[92:95]
	v_mfma_f32_16x16x32_bf16 v[88:91], v[140:143], v[180:183], v[88:91]
	v_mfma_f32_16x16x32_bf16 v[76:79], v[132:135], v[188:191], v[76:79]
	v_mfma_f32_16x16x32_bf16 v[72:75], v[140:143], v[188:191], v[72:75]
	v_mfma_f32_16x16x32_bf16 v[116:119], v[144:147], v[160:163], v[116:119]
	v_mfma_f32_16x16x32_bf16 v[112:115], v[152:155], v[160:163], v[112:115]
	v_mfma_f32_16x16x32_bf16 v[100:103], v[144:147], v[168:171], v[100:103]
	v_mfma_f32_16x16x32_bf16 v[96:99], v[152:155], v[168:171], v[96:99]
	v_mfma_f32_16x16x32_bf16 v[84:87], v[144:147], v[176:179], v[84:87]
	v_mfma_f32_16x16x32_bf16 v[80:83], v[152:155], v[176:179], v[80:83]
	v_mfma_f32_16x16x32_bf16 v[68:71], v[144:147], v[184:187], v[68:71]
	v_mfma_f32_16x16x32_bf16 v[64:67], v[152:155], v[184:187], v[64:67]
	v_mfma_f32_16x16x32_bf16 v[116:119], v[148:151], v[164:167], v[116:119]
	v_mfma_f32_16x16x32_bf16 v[112:115], v[156:159], v[164:167], v[112:115]
	v_mfma_f32_16x16x32_bf16 v[100:103], v[148:151], v[172:175], v[100:103]
	v_mfma_f32_16x16x32_bf16 v[96:99], v[156:159], v[172:175], v[96:99]
	v_mfma_f32_16x16x32_bf16 v[84:87], v[148:151], v[180:183], v[84:87]
	v_mfma_f32_16x16x32_bf16 v[80:83], v[156:159], v[180:183], v[80:83]
	v_mfma_f32_16x16x32_bf16 v[68:71], v[148:151], v[188:191], v[68:71]
	v_mfma_f32_16x16x32_bf16 v[64:67], v[156:159], v[188:191], v[64:67]
	s_barrier
; #define PG8_STAGE(bufoff, gbase, voff) do { _Pragma("unroll") for (int _i = 0; _i < 2; ++_i) \
;         __builtin_amdgcn_global_load_lds((const unsigned*)((const char*)(gbase) + (voff)[_i]), (PG8_LAS unsigned*)(lds + (bufoff) + ldsw + _i * 8192), 16, 0, 0); } while (0)
; #define PG8_LDA(dst, b, h) do { _Pragma("unroll") for (int m = 0; m < 4; ++m) _Pragma("unroll") for (int k = 0; k < 2; ++k) dst[m][k] = *(const PG8_LAS bf16x8*)(lds + PG8_SA(b, h) + aoff + m * 2048 + k * 1024); } while (0)
; #define PG8_MMA(ai, bj, At, Bt) do { __builtin_amdgcn_s_setprio(1); _Pragma("unroll") for (int m = 0; m < 4; ++m) _Pragma("unroll") for (int n = 0; n < 2; ++n) _Pragma("unroll") for (int k = 0; k < 2; ++k) \
;         acc[ai][bj][m][n] = __builtin_amdgcn_mfma_f32_16x16x32_bf16(Bt[n][k], At[m][k], acc[ai][bj][m][n], 0, 0, 0); __builtin_amdgcn_s_setprio(0); } while (0)
; #define PG8_WAIT_V(n) asm volatile("s_waitcnt vmcnt(" #n ")" ::: "memory")
; #define PG8_WAIT_L(n) asm volatile("s_waitcnt lgkmcnt(" #n ")" ::: "memory")
; #define PG8_BAR __builtin_amdgcn_s_barrier()
; #define PG8_SCHED __builtin_amdgcn_sched_barrier(0)
; template <class Epi, class Sched, bool ALIGN_EPI = false, bool SP2 = true>
; __device__ __forceinline__ void gemm_phase(PG8_LAS unsigned char* lds, const Gemm g, const Sched& S, const Epi& E) {
;     ...
;             PG8_LDA(At, 1, 1); PG8_STAGE(PG8_SB(1, 0), b3, voffB); PG8_STAGE(PG8_SB(1, 1), b3 + hstep, voffB); PG8_STAGE(PG8_SA(1, 0), a3, voffA);
;             PG8_WAIT_V(8); PG8_WAIT_L(0); PG8_BAR; PG8_MMA(1, 0, At, B0); PG8_MMA(1, 1, At, B1); PG8_BAR; PG8_SCHED;
;     ...
;         }
;         if constexpr (ALIGN_EPI) { if (wr == 0) PG8_BAR; }
	s_setprio 0
	s_add_i32 s4, s4, s57
	v_lshl_add_u64 v[212:213], v[212:213], 0, s[18:19]
	s_mov_b32 m0, s4
	ds_read_b128 v[160:163], v237 offset:49152
	ds_read_b128 v[164:167], v237 offset:50176
	ds_read_b128 v[168:171], v237 offset:51200
	ds_read_b128 v[172:175], v237 offset:52224
	ds_read_b128 v[176:179], v237 offset:53248
	ds_read_b128 v[180:183], v237 offset:54272
	ds_read_b128 v[184:187], v237 offset:55296
	ds_read_b128 v[188:191], v237 offset:56320
	global_load_lds_dwordx4 v[212:213], off
	s_add_i32 m0, s4, 0x2000
	s_add_u32 s14, vcc_lo, 0xb0080
	v_lshl_add_u64 v[212:213], v[214:215], 0, s[18:19]
	s_addc_u32 s15, vcc_hi, 0
	s_add_i32 s4, s5, s57
	global_load_lds_dwordx4 v[212:213], off
	v_lshl_add_u64 v[212:213], s[14:15], 0, v[194:195]
	s_mov_b32 m0, s4
	s_nop 0
	global_load_lds_dwordx4 v[212:213], off
	v_lshl_add_u64 v[212:213], s[14:15], 0, v[204:205]
	s_add_i32 m0, s4, 0x2000
	s_nop 0
	global_load_lds_dwordx4 v[212:213], off
	v_lshl_add_u64 v[212:213], s[46:47], 0, v[200:201]
	s_mov_b32 m0, s34
	s_nop 0
	global_load_lds_dwordx4 v[212:213], off
	v_lshl_add_u64 v[212:213], s[46:47], 0, v[202:203]
	s_mov_b32 m0, s35
	s_nop 0
	global_load_lds_dwordx4 v[212:213], off
	s_waitcnt vmcnt(8)
	s_waitcnt lgkmcnt(0)
	s_setprio 1
	s_barrier
	v_mfma_f32_16x16x32_bf16 v[60:63], v[128:131], v[160:163], v[60:63]
	v_mfma_f32_16x16x32_bf16 v[56:59], v[136:139], v[160:163], v[56:59]
	v_mfma_f32_16x16x32_bf16 v[44:47], v[128:131], v[168:171], v[44:47]
	v_mfma_f32_16x16x32_bf16 v[40:43], v[136:139], v[168:171], v[40:43]
	v_mfma_f32_16x16x32_bf16 v[28:31], v[128:131], v[176:179], v[28:31]
	v_mfma_f32_16x16x32_bf16 v[24:27], v[136:139], v[176:179], v[24:27]
	v_mfma_f32_16x16x32_bf16 v[12:15], v[128:131], v[184:187], v[12:15]
	v_mfma_f32_16x16x32_bf16 v[8:11], v[136:139], v[184:187], v[8:11]
	v_mfma_f32_16x16x32_bf16 v[60:63], v[132:135], v[164:167], v[60:63]
	v_mfma_f32_16x16x32_bf16 v[56:59], v[140:143], v[164:167], v[56:59]
	v_mfma_f32_16x16x32_bf16 v[44:47], v[132:135], v[172:175], v[44:47]
	v_mfma_f32_16x16x32_bf16 v[40:43], v[140:143], v[172:175], v[40:43]
	v_mfma_f32_16x16x32_bf16 v[28:31], v[132:135], v[180:183], v[28:31]
	v_mfma_f32_16x16x32_bf16 v[24:27], v[140:143], v[180:183], v[24:27]
	v_mfma_f32_16x16x32_bf16 v[12:15], v[132:135], v[188:191], v[12:15]
	v_mfma_f32_16x16x32_bf16 v[8:11], v[140:143], v[188:191], v[8:11]
	v_mfma_f32_16x16x32_bf16 v[52:55], v[144:147], v[160:163], v[52:55]
	v_mfma_f32_16x16x32_bf16 v[48:51], v[152:155], v[160:163], v[48:51]
	v_mfma_f32_16x16x32_bf16 v[36:39], v[144:147], v[168:171], v[36:39]
	v_mfma_f32_16x16x32_bf16 v[32:35], v[152:155], v[168:171], v[32:35]
	v_mfma_f32_16x16x32_bf16 v[20:23], v[144:147], v[176:179], v[20:23]
	v_mfma_f32_16x16x32_bf16 v[16:19], v[152:155], v[176:179], v[16:19]
	v_mfma_f32_16x16x32_bf16 v[4:7], v[144:147], v[184:187], v[4:7]
	v_mfma_f32_16x16x32_bf16 v[0:3], v[152:155], v[184:187], v[0:3]
	v_mfma_f32_16x16x32_bf16 v[52:55], v[148:151], v[164:167], v[52:55]
	v_mfma_f32_16x16x32_bf16 v[48:51], v[156:159], v[164:167], v[48:51]
	v_mfma_f32_16x16x32_bf16 v[36:39], v[148:151], v[172:175], v[36:39]
	v_mfma_f32_16x16x32_bf16 v[32:35], v[156:159], v[172:175], v[32:35]
	v_mfma_f32_16x16x32_bf16 v[20:23], v[148:151], v[180:183], v[20:23]
	v_mfma_f32_16x16x32_bf16 v[16:19], v[156:159], v[180:183], v[16:19]
	v_mfma_f32_16x16x32_bf16 v[4:7], v[148:151], v[188:191], v[4:7]
	v_mfma_f32_16x16x32_bf16 v[0:3], v[156:159], v[188:191], v[0:3]
	s_barrier
	s_setprio 0
	s_add_i32 s7, s7, 2
	s_add_u32 s42, s42, 0x10000
	s_addc_u32 s43, s43, 0
	s_add_u32 s17, s17, 0x100
	s_addc_u32 s6, s6, 0
	s_cmp_gt_u32 s7, 41
	s_cbranch_scc0 .LBB0_236
	s_and_b64 vcc, exec, s[48:49]
	s_cbranch_vccz .LBB0_239
	s_barrier

; #define PG8_STAGE(bufoff, gbase, voff) do { _Pragma("unroll") for (int _i = 0; _i < 2; ++_i) \
;         __builtin_amdgcn_global_load_lds((const unsigned*)((const char*)(gbase) + (voff)[_i]), (PG8_LAS unsigned*)(lds + (bufoff) + ldsw + _i * 8192), 16, 0, 0); } while (0)
; #define PG8_LDA(dst, b, h) do { _Pragma("unroll") for (int m = 0; m < 4; ++m) _Pragma("unroll") for (int k = 0; k < 2; ++k) dst[m][k] = *(const PG8_LAS bf16x8*)(lds + PG8_SA(b, h) + aoff + m * 2048 + k * 1024); } while (0)
; #define PG8_LDB(dst, b, h) do { _Pragma("unroll") for (int n = 0; n < 2; ++n) _Pragma("unroll") for (int k = 0; k < 2; ++k) dst[n][k] = *(const PG8_LAS bf16x8*)(lds + PG8_SB(b, h) + boff + n * 2048 + k * 1024); } while (0)
; #define PG8_MMA(ai, bj, At, Bt) do { __builtin_amdgcn_s_setprio(1); _Pragma("unroll") for (int m = 0; m < 4; ++m) _Pragma("unroll") for (int n = 0; n < 2; ++n) _Pragma("unroll") for (int k = 0; k < 2; ++k) \
;         acc[ai][bj][m][n] = __builtin_amdgcn_mfma_f32_16x16x32_bf16(Bt[n][k], At[m][k], acc[ai][bj][m][n], 0, 0, 0); __builtin_amdgcn_s_setprio(0); } while (0)
; #define PG8_WAIT_V(n) asm volatile("s_waitcnt vmcnt(" #n ")" ::: "memory")
; #define PG8_WAIT_L(n) asm volatile("s_waitcnt lgkmcnt(" #n ")" ::: "memory")
; template <class Epi, class Sched, bool ALIGN_EPI = false, bool SP2 = true>
; __device__ __forceinline__ void gemm_phase(PG8_LAS unsigned char* lds, const Gemm g, const Sched& S, const Epi& E) {
;     ...
;             const bool last = (t == nt - 2);
;             const char* a1 = cA + (size_t)(t + 1) * kstepA;
;             const char* a2 = last ? nA : cA + (size_t)(t + 2) * kstepA; const char* b2 = last ? nB : cB + (size_t)(t + 2) * kstep;
;             const char* a3 = a2 + kstepA; const char* b3 = b2 + kstep;
;             if (last && has_next) S.a_ready(nxt);
;             if constexpr (SP2) {
;             PG8_LDB(B0, 0, 0); PG8_LDB(B1, 0, 1); PG8_SCHED; PG8_LDA(At, 0, 0); PG8_STAGE(PG8_SA(1, 1), a1 + hstepA, voffA);
;             PG8_WAIT_V(8); PG8_WAIT_L(0); PG8_BAR; PG8_MMA(0, 0, At, B0); PG8_MMA(0, 1, At, B1); PG8_BAR; PG8_SCHED;
;             PG8_LDA(At, 0, 1); PG8_STAGE(PG8_SB(0, 0), b2, voffB); PG8_STAGE(PG8_SB(0, 1), b2 + hstep, voffB); PG8_STAGE(PG8_SA(0, 0), a2, voffA);
;             PG8_WAIT_V(8); PG8_WAIT_L(0); PG8_BAR; PG8_MMA(1, 0, At, B0); PG8_MMA(1, 1, At, B1); PG8_BAR; PG8_SCHED;
.LBB0_376:
	s_add_u32 s4, s52, 0xfffc0080
	s_addc_u32 s5, s53, -1
	s_add_i32 s14, 0, 0x10000
	s_cmp_eq_u32 s59, 12
	s_cselect_b32 s85, s16, s5
	s_cselect_b32 s84, s17, s4
	v_add_u32_e32 v138, s14, v145
	s_cselect_b32 s47, s39, s7
	s_cselect_b32 s46, s41, s6
	s_add_i32 s4, 0, 0x14000
	ds_read_b128 v[150:153], v138
	ds_read_b128 v[154:157], v138 offset:1024
	ds_read_b128 v[158:161], v138 offset:2048
	ds_read_b128 v[162:165], v138 offset:3072
	v_add_u32_e32 v138, s4, v145
	ds_read_b128 v[166:169], v138
	ds_read_b128 v[170:173], v138 offset:1024
	ds_read_b128 v[174:177], v138 offset:2048
	ds_read_b128 v[178:181], v138 offset:3072
	v_lshl_add_u64 v[138:139], s[52:53], 0, v[134:135]
	s_add_i32 m0, s31, 0xc000
	ds_read_b128 v[182:185], v149
	ds_read_b128 v[186:189], v149 offset:1024
	ds_read_b128 v[200:203], v149 offset:2048
	ds_read_b128 v[204:207], v149 offset:3072
	ds_read_b128 v[208:211], v149 offset:4096
	ds_read_b128 v[212:215], v149 offset:5120
	ds_read_b128 v[216:219], v149 offset:6144
	ds_read_b128 v[220:223], v149 offset:7168
	global_load_lds_dwordx4 v[138:139], off
	v_lshl_add_u64 v[138:139], s[52:53], 0, v[136:137]
	s_add_i32 m0, s31, 0xe000
	s_nop 0
	global_load_lds_dwordx4 v[138:139], off
	s_waitcnt vmcnt(8)
	s_waitcnt lgkmcnt(0)
	s_setprio 1
	s_barrier
	v_mfma_f32_16x16x32_bf16 v[124:127], v[150:153], v[182:185], v[124:127]
	v_mfma_f32_16x16x32_bf16 v[120:123], v[158:161], v[182:185], v[120:123]
	v_mfma_f32_16x16x32_bf16 v[112:115], v[150:153], v[200:203], v[112:115]
	v_mfma_f32_16x16x32_bf16 v[104:107], v[158:161], v[200:203], v[104:107]
	v_mfma_f32_16x16x32_bf16 v[96:99], v[150:153], v[208:211], v[96:99]
	v_mfma_f32_16x16x32_bf16 v[88:91], v[158:161], v[208:211], v[88:91]
	v_mfma_f32_16x16x32_bf16 v[80:83], v[150:153], v[216:219], v[80:83]
	v_mfma_f32_16x16x32_bf16 v[72:75], v[158:161], v[216:219], v[72:75]
	v_mfma_f32_16x16x32_bf16 v[124:127], v[154:157], v[186:189], v[124:127]
	v_mfma_f32_16x16x32_bf16 v[120:123], v[162:165], v[186:189], v[120:123]
	v_mfma_f32_16x16x32_bf16 v[112:115], v[154:157], v[204:207], v[112:115]
	v_mfma_f32_16x16x32_bf16 v[104:107], v[162:165], v[204:207], v[104:107]
	v_mfma_f32_16x16x32_bf16 v[96:99], v[154:157], v[212:215], v[96:99]
	v_mfma_f32_16x16x32_bf16 v[88:91], v[162:165], v[212:215], v[88:91]
	v_mfma_f32_16x16x32_bf16 v[80:83], v[154:157], v[220:223], v[80:83]
	v_mfma_f32_16x16x32_bf16 v[72:75], v[162:165], v[220:223], v[72:75]
	v_mfma_f32_16x16x32_bf16 v[116:119], v[166:169], v[182:185], v[116:119]
	v_mfma_f32_16x16x32_bf16 v[108:111], v[174:177], v[182:185], v[108:111]
	v_mfma_f32_16x16x32_bf16 v[100:103], v[166:169], v[200:203], v[100:103]
	v_mfma_f32_16x16x32_bf16 v[92:95], v[174:177], v[200:203], v[92:95]
	v_mfma_f32_16x16x32_bf16 v[84:87], v[166:169], v[208:211], v[84:87]
	v_mfma_f32_16x16x32_bf16 v[76:79], v[174:177], v[208:211], v[76:79]
	v_mfma_f32_16x16x32_bf16 v[68:71], v[166:169], v[216:219], v[68:71]
	v_mfma_f32_16x16x32_bf16 v[64:67], v[174:177], v[216:219], v[64:67]
	v_mfma_f32_16x16x32_bf16 v[116:119], v[170:173], v[186:189], v[116:119]
	v_mfma_f32_16x16x32_bf16 v[108:111], v[178:181], v[186:189], v[108:111]
	v_mfma_f32_16x16x32_bf16 v[100:103], v[170:173], v[204:207], v[100:103]
	v_mfma_f32_16x16x32_bf16 v[92:95], v[178:181], v[204:207], v[92:95]
	v_mfma_f32_16x16x32_bf16 v[84:87], v[170:173], v[212:215], v[84:87]
	v_mfma_f32_16x16x32_bf16 v[76:79], v[178:181], v[212:215], v[76:79]
	v_mfma_f32_16x16x32_bf16 v[68:71], v[170:173], v[220:223], v[68:71]
	v_mfma_f32_16x16x32_bf16 v[64:67], v[178:181], v[220:223], v[64:67]
	s_barrier
	s_setprio 0
	s_add_i32 s5, s14, s28
	v_lshl_add_u64 v[138:139], s[46:47], 0, v[194:195]
	s_mov_b32 m0, s5
	ds_read_b128 v[182:185], v149 offset:16384
	ds_read_b128 v[186:189], v149 offset:17408
	ds_read_b128 v[200:203], v149 offset:18432
	ds_read_b128 v[204:207], v149 offset:19456
	ds_read_b128 v[208:211], v149 offset:20480
	ds_read_b128 v[212:215], v149 offset:21504
	ds_read_b128 v[216:219], v149 offset:22528
	ds_read_b128 v[220:223], v149 offset:23552
	global_load_lds_dwordx4 v[138:139], off
	s_add_i32 m0, s5, 0x2000
	s_add_u32 s14, s46, 0x40000
	v_lshl_add_u64 v[142:143], s[46:47], 0, v[128:129]
	s_addc_u32 s15, s47, 0
	s_add_i32 s4, s4, s28
	global_load_lds_dwordx4 v[142:143], off
	v_lshl_add_u64 v[190:191], s[14:15], 0, v[194:195]
	s_mov_b32 m0, s4
	v_lshl_add_u64 v[224:225], s[84:85], 0, v[130:131]
	global_load_lds_dwordx4 v[190:191], off
	v_lshl_add_u64 v[190:191], s[14:15], 0, v[128:129]
	s_add_i32 m0, s4, 0x2000
	s_nop 0
	global_load_lds_dwordx4 v[190:191], off
	v_lshl_add_u64 v[190:191], s[84:85], 0, v[132:133]
	s_mov_b32 m0, s31
	s_nop 0
	global_load_lds_dwordx4 v[190:191], off
	s_mov_b32 m0, s34
	s_nop 0
	global_load_lds_dwordx4 v[224:225], off
	s_waitcnt vmcnt(8)
	s_waitcnt lgkmcnt(0)
	s_setprio 1
	s_barrier
; #define PG8_STAGE(bufoff, gbase, voff) do { _Pragma("unroll") for (int _i = 0; _i < 2; ++_i) \
;         __builtin_amdgcn_global_load_lds((const unsigned*)((const char*)(gbase) + (voff)[_i]), (PG8_LAS unsigned*)(lds + (bufoff) + ldsw + _i * 8192), 16, 0, 0); } while (0)
; #define PG8_LDA(dst, b, h) do { _Pragma("unroll") for (int m = 0; m < 4; ++m) _Pragma("unroll") for (int k = 0; k < 2; ++k) dst[m][k] = *(const PG8_LAS bf16x8*)(lds + PG8_SA(b, h) + aoff + m * 2048 + k * 1024); } while (0)
; #define PG8_LDB(dst, b, h) do { _Pragma("unroll") for (int n = 0; n < 2; ++n) _Pragma("unroll") for (int k = 0; k < 2; ++k) dst[n][k] = *(const PG8_LAS bf16x8*)(lds + PG8_SB(b, h) + boff + n * 2048 + k * 1024); } while (0)
; #define PG8_MMA(ai, bj, At, Bt) do { __builtin_amdgcn_s_setprio(1); _Pragma("unroll") for (int m = 0; m < 4; ++m) _Pragma("unroll") for (int n = 0; n < 2; ++n) _Pragma("unroll") for (int k = 0; k < 2; ++k) \
;         acc[ai][bj][m][n] = __builtin_amdgcn_mfma_f32_16x16x32_bf16(Bt[n][k], At[m][k], acc[ai][bj][m][n], 0, 0, 0); __builtin_amdgcn_s_setprio(0); } while (0)
; #define PG8_WAIT_V(n) asm volatile("s_waitcnt vmcnt(" #n ")" ::: "memory")
; #define PG8_WAIT_L(n) asm volatile("s_waitcnt lgkmcnt(" #n ")" ::: "memory")
; #define PG8_BAR __builtin_amdgcn_s_barrier()
; #define PG8_SCHED __builtin_amdgcn_sched_barrier(0)
; template <class Epi, class Sched, bool ALIGN_EPI = false, bool SP2 = true>
; __device__ __forceinline__ void gemm_phase(PG8_LAS unsigned char* lds, const Gemm g, const Sched& S, const Epi& E) {
;     ...
;             PG8_WAIT_V(8); PG8_WAIT_L(0); PG8_BAR; PG8_MMA(1, 0, At, B0); PG8_MMA(1, 1, At, B1); PG8_BAR; PG8_SCHED;
;             PG8_LDB(B0, 1, 0); PG8_LDB(B1, 1, 1); PG8_SCHED; PG8_LDA(At, 1, 0); PG8_STAGE(PG8_SA(0, 1), a2 + hstepA, voffA);
;             PG8_WAIT_V(8); PG8_WAIT_L(0); PG8_BAR; PG8_MMA(0, 0, At, B0); PG8_MMA(0, 1, At, B1); PG8_BAR; PG8_SCHED;
;             PG8_LDA(At, 1, 1); PG8_STAGE(PG8_SB(1, 0), b3, voffB); PG8_STAGE(PG8_SB(1, 1), b3 + hstep, voffB); PG8_STAGE(PG8_SA(1, 0), a3, voffA);
;             PG8_WAIT_V(8); PG8_WAIT_L(0); PG8_BAR; PG8_MMA(1, 0, At, B0); PG8_MMA(1, 1, At, B1); PG8_BAR; PG8_SCHED;
	v_mfma_f32_16x16x32_bf16 v[60:63], v[150:153], v[182:185], v[60:63]
	v_mfma_f32_16x16x32_bf16 v[56:59], v[158:161], v[182:185], v[56:59]
	v_mfma_f32_16x16x32_bf16 v[48:51], v[150:153], v[200:203], v[48:51]
	v_mfma_f32_16x16x32_bf16 v[40:43], v[158:161], v[200:203], v[40:43]
	v_mfma_f32_16x16x32_bf16 v[32:35], v[150:153], v[208:211], v[32:35]
	v_mfma_f32_16x16x32_bf16 v[24:27], v[158:161], v[208:211], v[24:27]
	v_mfma_f32_16x16x32_bf16 v[16:19], v[150:153], v[216:219], v[16:19]
	v_mfma_f32_16x16x32_bf16 v[8:11], v[158:161], v[216:219], v[8:11]
	v_mfma_f32_16x16x32_bf16 v[60:63], v[154:157], v[186:189], v[60:63]
	v_mfma_f32_16x16x32_bf16 v[56:59], v[162:165], v[186:189], v[56:59]
	v_mfma_f32_16x16x32_bf16 v[48:51], v[154:157], v[204:207], v[48:51]
	v_mfma_f32_16x16x32_bf16 v[40:43], v[162:165], v[204:207], v[40:43]
	v_mfma_f32_16x16x32_bf16 v[32:35], v[154:157], v[212:215], v[32:35]
	v_mfma_f32_16x16x32_bf16 v[24:27], v[162:165], v[212:215], v[24:27]
	v_mfma_f32_16x16x32_bf16 v[16:19], v[154:157], v[220:223], v[16:19]
	v_mfma_f32_16x16x32_bf16 v[8:11], v[162:165], v[220:223], v[8:11]
	v_mfma_f32_16x16x32_bf16 v[52:55], v[166:169], v[182:185], v[52:55]
	v_mfma_f32_16x16x32_bf16 v[44:47], v[174:177], v[182:185], v[44:47]
	v_mfma_f32_16x16x32_bf16 v[36:39], v[166:169], v[200:203], v[36:39]
	v_mfma_f32_16x16x32_bf16 v[28:31], v[174:177], v[200:203], v[28:31]
	v_mfma_f32_16x16x32_bf16 v[20:23], v[166:169], v[208:211], v[20:23]
	v_mfma_f32_16x16x32_bf16 v[12:15], v[174:177], v[208:211], v[12:15]
	v_mfma_f32_16x16x32_bf16 v[4:7], v[166:169], v[216:219], v[4:7]
	v_mfma_f32_16x16x32_bf16 v[0:3], v[174:177], v[216:219], v[0:3]
	v_mfma_f32_16x16x32_bf16 v[52:55], v[170:173], v[186:189], v[52:55]
	v_mfma_f32_16x16x32_bf16 v[44:47], v[178:181], v[186:189], v[44:47]
	v_mfma_f32_16x16x32_bf16 v[36:39], v[170:173], v[204:207], v[36:39]
	v_mfma_f32_16x16x32_bf16 v[28:31], v[178:181], v[204:207], v[28:31]
	v_mfma_f32_16x16x32_bf16 v[20:23], v[170:173], v[212:215], v[20:23]
	v_mfma_f32_16x16x32_bf16 v[12:15], v[178:181], v[212:215], v[12:15]
	v_mfma_f32_16x16x32_bf16 v[4:7], v[170:173], v[220:223], v[4:7]
	v_mfma_f32_16x16x32_bf16 v[0:3], v[178:181], v[220:223], v[0:3]
	s_barrier
	s_setprio 0
	s_add_i32 s4, 0, 0x18000
	v_add_u32_e32 v140, s4, v145
	s_add_i32 s5, 0, 0x1c000
	ds_read_b128 v[150:153], v140
	ds_read_b128 v[154:157], v140 offset:1024
	ds_read_b128 v[158:161], v140 offset:2048
	ds_read_b128 v[162:165], v140 offset:3072
	v_add_u32_e32 v140, s5, v145
	ds_read_b128 v[166:169], v140
	ds_read_b128 v[170:173], v140 offset:1024
	ds_read_b128 v[174:177], v140 offset:2048
	ds_read_b128 v[178:181], v140 offset:3072
	s_add_u32 s14, s84, 0x40000
	s_addc_u32 s15, s85, 0
	s_mov_b32 m0, s35
	v_lshl_add_u64 v[226:227], s[14:15], 0, v[132:133]
	ds_read_b128 v[182:185], v149 offset:32768
	ds_read_b128 v[186:189], v149 offset:33792
	ds_read_b128 v[200:203], v149 offset:34816
	ds_read_b128 v[204:207], v149 offset:35840
	ds_read_b128 v[208:211], v149 offset:36864
	ds_read_b128 v[212:215], v149 offset:37888
	ds_read_b128 v[216:219], v149 offset:38912
	ds_read_b128 v[220:223], v149 offset:39936
	global_load_lds_dwordx4 v[226:227], off
	v_lshl_add_u64 v[226:227], s[14:15], 0, v[130:131]
	s_mov_b32 m0, s49
	s_nop 0
	global_load_lds_dwordx4 v[226:227], off
	s_waitcnt vmcnt(8)
	s_waitcnt lgkmcnt(0)
	s_setprio 1
	s_barrier
	v_mfma_f32_16x16x32_bf16 v[124:127], v[150:153], v[182:185], v[124:127]
	v_mfma_f32_16x16x32_bf16 v[120:123], v[158:161], v[182:185], v[120:123]
	v_mfma_f32_16x16x32_bf16 v[112:115], v[150:153], v[200:203], v[112:115]
	v_mfma_f32_16x16x32_bf16 v[104:107], v[158:161], v[200:203], v[104:107]
	v_mfma_f32_16x16x32_bf16 v[96:99], v[150:153], v[208:211], v[96:99]
	v_mfma_f32_16x16x32_bf16 v[88:91], v[158:161], v[208:211], v[88:91]
	v_mfma_f32_16x16x32_bf16 v[80:83], v[150:153], v[216:219], v[80:83]
	v_mfma_f32_16x16x32_bf16 v[72:75], v[158:161], v[216:219], v[72:75]
	v_mfma_f32_16x16x32_bf16 v[124:127], v[154:157], v[186:189], v[124:127]
	v_mfma_f32_16x16x32_bf16 v[120:123], v[162:165], v[186:189], v[120:123]
	v_mfma_f32_16x16x32_bf16 v[112:115], v[154:157], v[204:207], v[112:115]
	v_mfma_f32_16x16x32_bf16 v[104:107], v[162:165], v[204:207], v[104:107]
	v_mfma_f32_16x16x32_bf16 v[96:99], v[154:157], v[212:215], v[96:99]
	v_mfma_f32_16x16x32_bf16 v[88:91], v[162:165], v[212:215], v[88:91]
	v_mfma_f32_16x16x32_bf16 v[80:83], v[154:157], v[220:223], v[80:83]
	v_mfma_f32_16x16x32_bf16 v[72:75], v[162:165], v[220:223], v[72:75]
	v_mfma_f32_16x16x32_bf16 v[116:119], v[166:169], v[182:185], v[116:119]
	v_mfma_f32_16x16x32_bf16 v[108:111], v[174:177], v[182:185], v[108:111]
	v_mfma_f32_16x16x32_bf16 v[100:103], v[166:169], v[200:203], v[100:103]
	v_mfma_f32_16x16x32_bf16 v[92:95], v[174:177], v[200:203], v[92:95]
	v_mfma_f32_16x16x32_bf16 v[84:87], v[166:169], v[208:211], v[84:87]
	v_mfma_f32_16x16x32_bf16 v[76:79], v[174:177], v[208:211], v[76:79]
	v_mfma_f32_16x16x32_bf16 v[68:71], v[166:169], v[216:219], v[68:71]
	v_mfma_f32_16x16x32_bf16 v[64:67], v[174:177], v[216:219], v[64:67]
	v_mfma_f32_16x16x32_bf16 v[116:119], v[170:173], v[186:189], v[116:119]
	v_mfma_f32_16x16x32_bf16 v[108:111], v[178:181], v[186:189], v[108:111]
	v_mfma_f32_16x16x32_bf16 v[100:103], v[170:173], v[204:207], v[100:103]
	v_mfma_f32_16x16x32_bf16 v[92:95], v[178:181], v[204:207], v[92:95]
	v_mfma_f32_16x16x32_bf16 v[84:87], v[170:173], v[212:215], v[84:87]
	v_mfma_f32_16x16x32_bf16 v[76:79], v[178:181], v[212:215], v[76:79]
	v_mfma_f32_16x16x32_bf16 v[68:71], v[170:173], v[220:223], v[68:71]
	v_mfma_f32_16x16x32_bf16 v[64:67], v[178:181], v[220:223], v[64:67]
	s_barrier
; #define PG8_STAGE(bufoff, gbase, voff) do { _Pragma("unroll") for (int _i = 0; _i < 2; ++_i) \
;         __builtin_amdgcn_global_load_lds((const unsigned*)((const char*)(gbase) + (voff)[_i]), (PG8_LAS unsigned*)(lds + (bufoff) + ldsw + _i * 8192), 16, 0, 0); } while (0)
; #define PG8_LDA(dst, b, h) do { _Pragma("unroll") for (int m = 0; m < 4; ++m) _Pragma("unroll") for (int k = 0; k < 2; ++k) dst[m][k] = *(const PG8_LAS bf16x8*)(lds + PG8_SA(b, h) + aoff + m * 2048 + k * 1024); } while (0)
; #define PG8_MMA(ai, bj, At, Bt) do { __builtin_amdgcn_s_setprio(1); _Pragma("unroll") for (int m = 0; m < 4; ++m) _Pragma("unroll") for (int n = 0; n < 2; ++n) _Pragma("unroll") for (int k = 0; k < 2; ++k) \
;         acc[ai][bj][m][n] = __builtin_amdgcn_mfma_f32_16x16x32_bf16(Bt[n][k], At[m][k], acc[ai][bj][m][n], 0, 0, 0); __builtin_amdgcn_s_setprio(0); } while (0)
; #define PG8_WAIT_V(n) asm volatile("s_waitcnt vmcnt(" #n ")" ::: "memory")
; #define PG8_WAIT_L(n) asm volatile("s_waitcnt lgkmcnt(" #n ")" ::: "memory")
; #define PG8_BAR __builtin_amdgcn_s_barrier()
; #define PG8_SCHED __builtin_amdgcn_sched_barrier(0)
; template <class Epi, class Sched, bool ALIGN_EPI = false, bool SP2 = true>
; __device__ __forceinline__ void gemm_phase(PG8_LAS unsigned char* lds, const Gemm g, const Sched& S, const Epi& E) {
;     ...
;             PG8_LDA(At, 1, 1); PG8_STAGE(PG8_SB(1, 0), b3, voffB); PG8_STAGE(PG8_SB(1, 1), b3 + hstep, voffB); PG8_STAGE(PG8_SA(1, 0), a3, voffA);
;             PG8_WAIT_V(8); PG8_WAIT_L(0); PG8_BAR; PG8_MMA(1, 0, At, B0); PG8_MMA(1, 1, At, B1); PG8_BAR; PG8_SCHED;
;     ...
;         }
;         if constexpr (ALIGN_EPI) { if (wr == 0) PG8_BAR; }
	s_setprio 0
	s_add_i32 s4, s4, s28
	v_lshl_add_u64 v[138:139], v[138:139], 0, s[18:19]
	s_mov_b32 m0, s4
	ds_read_b128 v[182:185], v149 offset:49152
	ds_read_b128 v[186:189], v149 offset:50176
	ds_read_b128 v[200:203], v149 offset:51200
	ds_read_b128 v[204:207], v149 offset:52224
	ds_read_b128 v[208:211], v149 offset:53248
	ds_read_b128 v[212:215], v149 offset:54272
	ds_read_b128 v[216:219], v149 offset:55296
	ds_read_b128 v[220:223], v149 offset:56320
	global_load_lds_dwordx4 v[138:139], off
	s_add_i32 m0, s4, 0x2000
	s_add_u32 s14, s46, 0x40080
	v_lshl_add_u64 v[138:139], v[142:143], 0, s[18:19]
	s_addc_u32 s15, s47, 0
	s_add_i32 s4, s5, s28
	global_load_lds_dwordx4 v[138:139], off
	v_lshl_add_u64 v[138:139], s[14:15], 0, v[194:195]
	s_mov_b32 m0, s4
	s_nop 0
	global_load_lds_dwordx4 v[138:139], off
	v_lshl_add_u64 v[138:139], s[14:15], 0, v[128:129]
	s_add_i32 m0, s4, 0x2000
	s_nop 0
	global_load_lds_dwordx4 v[138:139], off
	v_lshl_add_u64 v[138:139], v[190:191], 0, s[18:19]
	s_mov_b32 m0, s51
	s_nop 0
	global_load_lds_dwordx4 v[138:139], off
	v_lshl_add_u64 v[138:139], v[224:225], 0, s[18:19]
	s_mov_b32 m0, s57
	s_nop 0
	global_load_lds_dwordx4 v[138:139], off
	s_waitcnt vmcnt(8)
	s_waitcnt lgkmcnt(0)
	s_setprio 1
	s_barrier
	v_mfma_f32_16x16x32_bf16 v[60:63], v[150:153], v[182:185], v[60:63]
	v_mfma_f32_16x16x32_bf16 v[56:59], v[158:161], v[182:185], v[56:59]
	v_mfma_f32_16x16x32_bf16 v[48:51], v[150:153], v[200:203], v[48:51]
	v_mfma_f32_16x16x32_bf16 v[40:43], v[158:161], v[200:203], v[40:43]
	v_mfma_f32_16x16x32_bf16 v[32:35], v[150:153], v[208:211], v[32:35]
	v_mfma_f32_16x16x32_bf16 v[24:27], v[158:161], v[208:211], v[24:27]
	v_mfma_f32_16x16x32_bf16 v[16:19], v[150:153], v[216:219], v[16:19]
	v_mfma_f32_16x16x32_bf16 v[8:11], v[158:161], v[216:219], v[8:11]
	v_mfma_f32_16x16x32_bf16 v[60:63], v[154:157], v[186:189], v[60:63]
	v_mfma_f32_16x16x32_bf16 v[56:59], v[162:165], v[186:189], v[56:59]
	v_mfma_f32_16x16x32_bf16 v[48:51], v[154:157], v[204:207], v[48:51]
	v_mfma_f32_16x16x32_bf16 v[40:43], v[162:165], v[204:207], v[40:43]
	v_mfma_f32_16x16x32_bf16 v[32:35], v[154:157], v[212:215], v[32:35]
	v_mfma_f32_16x16x32_bf16 v[24:27], v[162:165], v[212:215], v[24:27]
	v_mfma_f32_16x16x32_bf16 v[16:19], v[154:157], v[220:223], v[16:19]
	v_mfma_f32_16x16x32_bf16 v[8:11], v[162:165], v[220:223], v[8:11]
	v_mfma_f32_16x16x32_bf16 v[52:55], v[166:169], v[182:185], v[52:55]
	v_mfma_f32_16x16x32_bf16 v[44:47], v[174:177], v[182:185], v[44:47]
	v_mfma_f32_16x16x32_bf16 v[36:39], v[166:169], v[200:203], v[36:39]
	v_mfma_f32_16x16x32_bf16 v[28:31], v[174:177], v[200:203], v[28:31]
	v_mfma_f32_16x16x32_bf16 v[20:23], v[166:169], v[208:211], v[20:23]
	v_mfma_f32_16x16x32_bf16 v[12:15], v[174:177], v[208:211], v[12:15]
	v_mfma_f32_16x16x32_bf16 v[4:7], v[166:169], v[216:219], v[4:7]
	v_mfma_f32_16x16x32_bf16 v[0:3], v[174:177], v[216:219], v[0:3]
	v_mfma_f32_16x16x32_bf16 v[52:55], v[170:173], v[186:189], v[52:55]
	v_mfma_f32_16x16x32_bf16 v[44:47], v[178:181], v[186:189], v[44:47]
	v_mfma_f32_16x16x32_bf16 v[36:39], v[170:173], v[204:207], v[36:39]
	v_mfma_f32_16x16x32_bf16 v[28:31], v[178:181], v[204:207], v[28:31]
	v_mfma_f32_16x16x32_bf16 v[20:23], v[170:173], v[212:215], v[20:23]
	v_mfma_f32_16x16x32_bf16 v[12:15], v[178:181], v[212:215], v[12:15]
	v_mfma_f32_16x16x32_bf16 v[4:7], v[170:173], v[220:223], v[4:7]
	v_mfma_f32_16x16x32_bf16 v[0:3], v[178:181], v[220:223], v[0:3]
	s_barrier
	s_setprio 0
	s_add_i32 s59, s59, 2
	s_add_u32 s52, s52, 0x100
	s_addc_u32 s53, s53, 0
	s_add_u32 s6, s6, 0x100
	s_addc_u32 s7, s7, 0
	s_cmp_gt_u32 s59, 13
	s_cbranch_scc0 .LBB0_376
	s_and_b64 vcc, exec, s[24:25]
	s_cbranch_vccz .LBB0_379
	s_barrier

; #define PG8_STAGE(bufoff, gbase, voff) do { _Pragma("unroll") for (int _i = 0; _i < 2; ++_i) \
;         __builtin_amdgcn_global_load_lds((const unsigned*)((const char*)(gbase) + (voff)[_i]), (PG8_LAS unsigned*)(lds + (bufoff) + ldsw + _i * 8192), 16, 0, 0); } while (0)
; #define PG8_LDA(dst, b, h) do { _Pragma("unroll") for (int m = 0; m < 4; ++m) _Pragma("unroll") for (int k = 0; k < 2; ++k) dst[m][k] = *(const PG8_LAS bf16x8*)(lds + PG8_SA(b, h) + aoff + m * 2048 + k * 1024); } while (0)
; #define PG8_LDB(dst, b, h) do { _Pragma("unroll") for (int n = 0; n < 2; ++n) _Pragma("unroll") for (int k = 0; k < 2; ++k) dst[n][k] = *(const PG8_LAS bf16x8*)(lds + PG8_SB(b, h) + boff + n * 2048 + k * 1024); } while (0)
; #define PG8_MMA(ai, bj, At, Bt) do { __builtin_amdgcn_s_setprio(1); _Pragma("unroll") for (int m = 0; m < 4; ++m) _Pragma("unroll") for (int n = 0; n < 2; ++n) _Pragma("unroll") for (int k = 0; k < 2; ++k) \
;         acc[ai][bj][m][n] = __builtin_amdgcn_mfma_f32_16x16x32_bf16(Bt[n][k], At[m][k], acc[ai][bj][m][n], 0, 0, 0); __builtin_amdgcn_s_setprio(0); } while (0)
; #define PG8_WAIT_V(n) asm volatile("s_waitcnt vmcnt(" #n ")" ::: "memory")
; #define PG8_WAIT_L(n) asm volatile("s_waitcnt lgkmcnt(" #n ")" ::: "memory")
; template <class Epi, class Sched, bool ALIGN_EPI = false, bool SP2 = true>
; __device__ __forceinline__ void gemm_phase(PG8_LAS unsigned char* lds, const Gemm g, const Sched& S, const Epi& E) {
;     ...
;             const bool last = (t == nt - 2);
;             const char* a1 = cA + (size_t)(t + 1) * kstepA;
;             const char* a2 = last ? nA : cA + (size_t)(t + 2) * kstepA; const char* b2 = last ? nB : cB + (size_t)(t + 2) * kstep;
;             const char* a3 = a2 + kstepA; const char* b3 = b2 + kstep;
;             if (last && has_next) S.a_ready(nxt);
;             if constexpr (SP2) {
;             PG8_LDB(B0, 0, 0); PG8_LDB(B1, 0, 1); PG8_SCHED; PG8_LDA(At, 0, 0); PG8_STAGE(PG8_SA(1, 1), a1 + hstepA, voffA);
;             PG8_WAIT_V(8); PG8_WAIT_L(0); PG8_BAR; PG8_MMA(0, 0, At, B0); PG8_MMA(0, 1, At, B1); PG8_BAR; PG8_SCHED;
;             PG8_LDA(At, 0, 1); PG8_STAGE(PG8_SB(0, 0), b2, voffB); PG8_STAGE(PG8_SB(0, 1), b2 + hstep, voffB); PG8_STAGE(PG8_SA(0, 0), a2, voffA);
;             PG8_WAIT_V(8); PG8_WAIT_L(0); PG8_BAR; PG8_MMA(1, 0, At, B0); PG8_MMA(1, 1, At, B1); PG8_BAR; PG8_SCHED;
.LBB0_540:
	s_add_u32 s4, s44, s6
	s_addc_u32 s5, s45, 0
	s_add_u32 s7, s4, 0x100
	s_addc_u32 s50, s5, 0
	s_and_b64 s[14:15], s[48:49], exec
	s_cselect_b32 s53, s39, s50
	s_cselect_b32 s52, s38, s7
	s_add_u32 s6, s42, s6
	s_addc_u32 s7, s43, 0
	s_add_u32 s14, s6, 0x100
	s_addc_u32 s15, s7, 0
	s_add_i32 s71, 0, 0x10000
	s_and_b64 s[6:7], s[48:49], exec
	s_cselect_b32 s97, s21, s15
	s_cselect_b32 s96, s25, s14
	s_add_i32 s14, 0, 0x14000
	s_add_u32 s84, s4, 0x40080
	s_addc_u32 s85, s5, 0
	s_add_i32 s4, s71, s26
	s_add_i32 m0, s27, 0xc000
	s_add_i32 s5, s27, 0xe000
	s_add_i32 s59, s4, 0x2000
	v_add_u32_e32 v134, s71, v137
	s_add_u32 vcc_lo, s96, 0x10000
	ds_read_b128 v[140:143], v134
	ds_read_b128 v[144:147], v134 offset:1024
	ds_read_b128 v[148:151], v134 offset:2048
	ds_read_b128 v[152:155], v134 offset:3072
	v_add_u32_e32 v134, s14, v137
	s_addc_u32 vcc_hi, s97, 0
	s_add_i32 s70, s14, s26
	ds_read_b128 v[156:159], v134
	ds_read_b128 v[160:163], v134 offset:1024
	ds_read_b128 v[164:167], v134 offset:2048
	ds_read_b128 v[168:171], v134 offset:3072
	s_add_i32 s60, s70, 0x2000
	s_add_i32 s58, 0, 0x18000
	s_add_i32 s57, 0, 0x1c000
	s_add_u32 s50, s52, 0x40000
	s_addc_u32 s51, s53, 0
	s_add_i32 s7, s58, s26
	s_add_i32 s6, s7, 0x2000
	s_add_u32 s48, s96, 0x10080
	s_addc_u32 s49, s97, 0
	s_add_i32 s15, s57, s26
	s_add_i32 s14, s15, 0x2000
	v_lshl_add_u64 v[134:135], s[84:85], 0, v[132:133]
	ds_read_b128 v[172:175], v139
	ds_read_b128 v[176:179], v139 offset:1024
	ds_read_b128 v[180:183], v139 offset:2048
	ds_read_b128 v[184:187], v139 offset:3072
	ds_read_b128 v[188:191], v139 offset:4096
	ds_read_b128 v[200:203], v139 offset:5120
	ds_read_b128 v[204:207], v139 offset:6144
	ds_read_b128 v[208:211], v139 offset:7168
	global_load_lds_dwordx4 v[134:135], off
	v_lshl_add_u64 v[134:135], s[84:85], 0, v[130:131]
	s_mov_b32 m0, s5
	s_nop 0
	global_load_lds_dwordx4 v[134:135], off
	s_waitcnt vmcnt(8)
	s_waitcnt lgkmcnt(0)
	s_setprio 1
	s_barrier
	v_mfma_f32_16x16x32_bf16 v[124:127], v[140:143], v[172:175], v[124:127]
	v_mfma_f32_16x16x32_bf16 v[120:123], v[148:151], v[172:175], v[120:123]
	v_mfma_f32_16x16x32_bf16 v[116:119], v[140:143], v[180:183], v[116:119]
	v_mfma_f32_16x16x32_bf16 v[108:111], v[148:151], v[180:183], v[108:111]
	v_mfma_f32_16x16x32_bf16 v[100:103], v[140:143], v[188:191], v[100:103]
	v_mfma_f32_16x16x32_bf16 v[92:95], v[148:151], v[188:191], v[92:95]
	v_mfma_f32_16x16x32_bf16 v[80:83], v[140:143], v[204:207], v[80:83]
	v_mfma_f32_16x16x32_bf16 v[72:75], v[148:151], v[204:207], v[72:75]
	v_mfma_f32_16x16x32_bf16 v[124:127], v[144:147], v[176:179], v[124:127]
	v_mfma_f32_16x16x32_bf16 v[120:123], v[152:155], v[176:179], v[120:123]
	v_mfma_f32_16x16x32_bf16 v[116:119], v[144:147], v[184:187], v[116:119]
	v_mfma_f32_16x16x32_bf16 v[108:111], v[152:155], v[184:187], v[108:111]
	v_mfma_f32_16x16x32_bf16 v[100:103], v[144:147], v[200:203], v[100:103]
	v_mfma_f32_16x16x32_bf16 v[92:95], v[152:155], v[200:203], v[92:95]
	v_mfma_f32_16x16x32_bf16 v[80:83], v[144:147], v[208:211], v[80:83]
	v_mfma_f32_16x16x32_bf16 v[72:75], v[152:155], v[208:211], v[72:75]
	v_mfma_f32_16x16x32_bf16 v[112:115], v[156:159], v[172:175], v[112:115]
	v_mfma_f32_16x16x32_bf16 v[104:107], v[164:167], v[172:175], v[104:107]
	v_mfma_f32_16x16x32_bf16 v[96:99], v[156:159], v[180:183], v[96:99]
	v_mfma_f32_16x16x32_bf16 v[88:91], v[164:167], v[180:183], v[88:91]
	v_mfma_f32_16x16x32_bf16 v[84:87], v[156:159], v[188:191], v[84:87]
	v_mfma_f32_16x16x32_bf16 v[76:79], v[164:167], v[188:191], v[76:79]
	v_mfma_f32_16x16x32_bf16 v[68:71], v[156:159], v[204:207], v[68:71]
	v_mfma_f32_16x16x32_bf16 v[64:67], v[164:167], v[204:207], v[64:67]
	v_mfma_f32_16x16x32_bf16 v[112:115], v[160:163], v[176:179], v[112:115]
	v_mfma_f32_16x16x32_bf16 v[104:107], v[168:171], v[176:179], v[104:107]
	v_mfma_f32_16x16x32_bf16 v[96:99], v[160:163], v[184:187], v[96:99]
	v_mfma_f32_16x16x32_bf16 v[88:91], v[168:171], v[184:187], v[88:91]
	v_mfma_f32_16x16x32_bf16 v[84:87], v[160:163], v[200:203], v[84:87]
	v_mfma_f32_16x16x32_bf16 v[76:79], v[168:171], v[200:203], v[76:79]
	v_mfma_f32_16x16x32_bf16 v[68:71], v[160:163], v[208:211], v[68:71]
	v_mfma_f32_16x16x32_bf16 v[64:67], v[168:171], v[208:211], v[64:67]
	s_barrier
	s_setprio 0
	s_mov_b32 m0, s4
	v_lshl_add_u64 v[134:135], s[96:97], 0, v[194:195]
	ds_read_b128 v[172:175], v139 offset:16384
	ds_read_b128 v[176:179], v139 offset:17408
	ds_read_b128 v[180:183], v139 offset:18432
	ds_read_b128 v[184:187], v139 offset:19456
	ds_read_b128 v[188:191], v139 offset:20480
	ds_read_b128 v[200:203], v139 offset:21504
	ds_read_b128 v[204:207], v139 offset:22528
	ds_read_b128 v[208:211], v139 offset:23552
	global_load_lds_dwordx4 v[134:135], off
	v_lshl_add_u64 v[198:199], s[96:97], 0, v[128:129]
	s_mov_b32 m0, s59
	v_lshl_add_u64 v[212:213], vcc, 0, v[194:195]
	global_load_lds_dwordx4 v[198:199], off
	s_mov_b32 m0, s70
	v_lshl_add_u64 v[214:215], s[52:53], 0, v[130:131]
	global_load_lds_dwordx4 v[212:213], off
	v_lshl_add_u64 v[212:213], vcc, 0, v[128:129]
	s_mov_b32 m0, s60
	s_nop 0
	global_load_lds_dwordx4 v[212:213], off
	v_lshl_add_u64 v[212:213], s[52:53], 0, v[132:133]
	s_mov_b32 m0, s27
	s_nop 0
	global_load_lds_dwordx4 v[212:213], off
	s_mov_b32 m0, s28
	s_nop 0
	global_load_lds_dwordx4 v[214:215], off
	s_waitcnt vmcnt(8)
	s_waitcnt lgkmcnt(0)
	s_setprio 1
	s_barrier
; #define PG8_STAGE(bufoff, gbase, voff) do { _Pragma("unroll") for (int _i = 0; _i < 2; ++_i) \
;         __builtin_amdgcn_global_load_lds((const unsigned*)((const char*)(gbase) + (voff)[_i]), (PG8_LAS unsigned*)(lds + (bufoff) + ldsw + _i * 8192), 16, 0, 0); } while (0)
; #define PG8_LDA(dst, b, h) do { _Pragma("unroll") for (int m = 0; m < 4; ++m) _Pragma("unroll") for (int k = 0; k < 2; ++k) dst[m][k] = *(const PG8_LAS bf16x8*)(lds + PG8_SA(b, h) + aoff + m * 2048 + k * 1024); } while (0)
; #define PG8_LDB(dst, b, h) do { _Pragma("unroll") for (int n = 0; n < 2; ++n) _Pragma("unroll") for (int k = 0; k < 2; ++k) dst[n][k] = *(const PG8_LAS bf16x8*)(lds + PG8_SB(b, h) + boff + n * 2048 + k * 1024); } while (0)
; #define PG8_MMA(ai, bj, At, Bt) do { __builtin_amdgcn_s_setprio(1); _Pragma("unroll") for (int m = 0; m < 4; ++m) _Pragma("unroll") for (int n = 0; n < 2; ++n) _Pragma("unroll") for (int k = 0; k < 2; ++k) \
;         acc[ai][bj][m][n] = __builtin_amdgcn_mfma_f32_16x16x32_bf16(Bt[n][k], At[m][k], acc[ai][bj][m][n], 0, 0, 0); __builtin_amdgcn_s_setprio(0); } while (0)
; #define PG8_WAIT_V(n) asm volatile("s_waitcnt vmcnt(" #n ")" ::: "memory")
; #define PG8_WAIT_L(n) asm volatile("s_waitcnt lgkmcnt(" #n ")" ::: "memory")
; #define PG8_BAR __builtin_amdgcn_s_barrier()
; #define PG8_SCHED __builtin_amdgcn_sched_barrier(0)
; template <class Epi, class Sched, bool ALIGN_EPI = false, bool SP2 = true>
; __device__ __forceinline__ void gemm_phase(PG8_LAS unsigned char* lds, const Gemm g, const Sched& S, const Epi& E) {
;     ...
;             PG8_WAIT_V(8); PG8_WAIT_L(0); PG8_BAR; PG8_MMA(1, 0, At, B0); PG8_MMA(1, 1, At, B1); PG8_BAR; PG8_SCHED;
;             PG8_LDB(B0, 1, 0); PG8_LDB(B1, 1, 1); PG8_SCHED; PG8_LDA(At, 1, 0); PG8_STAGE(PG8_SA(0, 1), a2 + hstepA, voffA);
;             PG8_WAIT_V(8); PG8_WAIT_L(0); PG8_BAR; PG8_MMA(0, 0, At, B0); PG8_MMA(0, 1, At, B1); PG8_BAR; PG8_SCHED;
;             PG8_LDA(At, 1, 1); PG8_STAGE(PG8_SB(1, 0), b3, voffB); PG8_STAGE(PG8_SB(1, 1), b3 + hstep, voffB); PG8_STAGE(PG8_SA(1, 0), a3, voffA);
;             PG8_WAIT_V(8); PG8_WAIT_L(0); PG8_BAR; PG8_MMA(1, 0, At, B0); PG8_MMA(1, 1, At, B1); PG8_BAR; PG8_SCHED;
	v_mfma_f32_16x16x32_bf16 v[60:63], v[140:143], v[172:175], v[60:63]
	v_mfma_f32_16x16x32_bf16 v[56:59], v[148:151], v[172:175], v[56:59]
	v_mfma_f32_16x16x32_bf16 v[52:55], v[140:143], v[180:183], v[52:55]
	v_mfma_f32_16x16x32_bf16 v[44:47], v[148:151], v[180:183], v[44:47]
	v_mfma_f32_16x16x32_bf16 v[36:39], v[140:143], v[188:191], v[36:39]
	v_mfma_f32_16x16x32_bf16 v[28:31], v[148:151], v[188:191], v[28:31]
	v_mfma_f32_16x16x32_bf16 v[20:23], v[140:143], v[204:207], v[20:23]
	v_mfma_f32_16x16x32_bf16 v[12:15], v[148:151], v[204:207], v[12:15]
	v_mfma_f32_16x16x32_bf16 v[60:63], v[144:147], v[176:179], v[60:63]
	v_mfma_f32_16x16x32_bf16 v[56:59], v[152:155], v[176:179], v[56:59]
	v_mfma_f32_16x16x32_bf16 v[52:55], v[144:147], v[184:187], v[52:55]
	v_mfma_f32_16x16x32_bf16 v[44:47], v[152:155], v[184:187], v[44:47]
	v_mfma_f32_16x16x32_bf16 v[36:39], v[144:147], v[200:203], v[36:39]
	v_mfma_f32_16x16x32_bf16 v[28:31], v[152:155], v[200:203], v[28:31]
	v_mfma_f32_16x16x32_bf16 v[20:23], v[144:147], v[208:211], v[20:23]
	v_mfma_f32_16x16x32_bf16 v[12:15], v[152:155], v[208:211], v[12:15]
	v_mfma_f32_16x16x32_bf16 v[48:51], v[156:159], v[172:175], v[48:51]
	v_mfma_f32_16x16x32_bf16 v[40:43], v[164:167], v[172:175], v[40:43]
	v_mfma_f32_16x16x32_bf16 v[32:35], v[156:159], v[180:183], v[32:35]
	v_mfma_f32_16x16x32_bf16 v[24:27], v[164:167], v[180:183], v[24:27]
	v_mfma_f32_16x16x32_bf16 v[16:19], v[156:159], v[188:191], v[16:19]
	v_mfma_f32_16x16x32_bf16 v[8:11], v[164:167], v[188:191], v[8:11]
	v_mfma_f32_16x16x32_bf16 v[4:7], v[156:159], v[204:207], v[4:7]
	v_mfma_f32_16x16x32_bf16 v[0:3], v[164:167], v[204:207], v[0:3]
	v_mfma_f32_16x16x32_bf16 v[48:51], v[160:163], v[176:179], v[48:51]
	v_mfma_f32_16x16x32_bf16 v[40:43], v[168:171], v[176:179], v[40:43]
	v_mfma_f32_16x16x32_bf16 v[32:35], v[160:163], v[184:187], v[32:35]
	v_mfma_f32_16x16x32_bf16 v[24:27], v[168:171], v[184:187], v[24:27]
	v_mfma_f32_16x16x32_bf16 v[16:19], v[160:163], v[200:203], v[16:19]
	v_mfma_f32_16x16x32_bf16 v[8:11], v[168:171], v[200:203], v[8:11]
	v_mfma_f32_16x16x32_bf16 v[4:7], v[160:163], v[208:211], v[4:7]
	v_mfma_f32_16x16x32_bf16 v[0:3], v[168:171], v[208:211], v[0:3]
	s_barrier
	s_setprio 0
	v_add_u32_e32 v152, s58, v137
	v_add_u32_e32 v168, s57, v137
	ds_read_b128 v[140:143], v152
	ds_read_b128 v[144:147], v152 offset:1024
	ds_read_b128 v[148:151], v152 offset:2048
	ds_read_b128 v[152:155], v152 offset:3072
	ds_read_b128 v[156:159], v168
	ds_read_b128 v[160:163], v168 offset:1024
	ds_read_b128 v[164:167], v168 offset:2048
	ds_read_b128 v[168:171], v168 offset:3072
	s_mov_b32 m0, s29
	v_lshl_add_u64 v[216:217], s[50:51], 0, v[132:133]
	ds_read_b128 v[172:175], v139 offset:32768
	ds_read_b128 v[176:179], v139 offset:33792
	ds_read_b128 v[180:183], v139 offset:34816
	ds_read_b128 v[184:187], v139 offset:35840
	ds_read_b128 v[188:191], v139 offset:36864
	ds_read_b128 v[200:203], v139 offset:37888
	ds_read_b128 v[204:207], v139 offset:38912
	ds_read_b128 v[208:211], v139 offset:39936
	global_load_lds_dwordx4 v[216:217], off
	v_lshl_add_u64 v[216:217], s[50:51], 0, v[130:131]
	s_mov_b32 m0, s30
	s_nop 0
	global_load_lds_dwordx4 v[216:217], off
	s_waitcnt vmcnt(8)
	s_waitcnt lgkmcnt(0)
	s_setprio 1
	s_barrier
	v_mfma_f32_16x16x32_bf16 v[124:127], v[140:143], v[172:175], v[124:127]
	v_mfma_f32_16x16x32_bf16 v[120:123], v[148:151], v[172:175], v[120:123]
	v_mfma_f32_16x16x32_bf16 v[116:119], v[140:143], v[180:183], v[116:119]
	v_mfma_f32_16x16x32_bf16 v[108:111], v[148:151], v[180:183], v[108:111]
	v_mfma_f32_16x16x32_bf16 v[100:103], v[140:143], v[188:191], v[100:103]
	v_mfma_f32_16x16x32_bf16 v[92:95], v[148:151], v[188:191], v[92:95]
	v_mfma_f32_16x16x32_bf16 v[80:83], v[140:143], v[204:207], v[80:83]
	v_mfma_f32_16x16x32_bf16 v[72:75], v[148:151], v[204:207], v[72:75]
	v_mfma_f32_16x16x32_bf16 v[124:127], v[144:147], v[176:179], v[124:127]
	v_mfma_f32_16x16x32_bf16 v[120:123], v[152:155], v[176:179], v[120:123]
	v_mfma_f32_16x16x32_bf16 v[116:119], v[144:147], v[184:187], v[116:119]
	v_mfma_f32_16x16x32_bf16 v[108:111], v[152:155], v[184:187], v[108:111]
	v_mfma_f32_16x16x32_bf16 v[100:103], v[144:147], v[200:203], v[100:103]
	v_mfma_f32_16x16x32_bf16 v[92:95], v[152:155], v[200:203], v[92:95]
	v_mfma_f32_16x16x32_bf16 v[80:83], v[144:147], v[208:211], v[80:83]
	v_mfma_f32_16x16x32_bf16 v[72:75], v[152:155], v[208:211], v[72:75]
	v_mfma_f32_16x16x32_bf16 v[112:115], v[156:159], v[172:175], v[112:115]
	v_mfma_f32_16x16x32_bf16 v[104:107], v[164:167], v[172:175], v[104:107]
	v_mfma_f32_16x16x32_bf16 v[96:99], v[156:159], v[180:183], v[96:99]
	v_mfma_f32_16x16x32_bf16 v[88:91], v[164:167], v[180:183], v[88:91]
	v_mfma_f32_16x16x32_bf16 v[84:87], v[156:159], v[188:191], v[84:87]
	v_mfma_f32_16x16x32_bf16 v[76:79], v[164:167], v[188:191], v[76:79]
	v_mfma_f32_16x16x32_bf16 v[68:71], v[156:159], v[204:207], v[68:71]
	v_mfma_f32_16x16x32_bf16 v[64:67], v[164:167], v[204:207], v[64:67]
	v_mfma_f32_16x16x32_bf16 v[112:115], v[160:163], v[176:179], v[112:115]
	v_mfma_f32_16x16x32_bf16 v[104:107], v[168:171], v[176:179], v[104:107]
	v_mfma_f32_16x16x32_bf16 v[96:99], v[160:163], v[184:187], v[96:99]
	v_mfma_f32_16x16x32_bf16 v[88:91], v[168:171], v[184:187], v[88:91]
	v_mfma_f32_16x16x32_bf16 v[84:87], v[160:163], v[200:203], v[84:87]
	v_mfma_f32_16x16x32_bf16 v[76:79], v[168:171], v[200:203], v[76:79]
	v_mfma_f32_16x16x32_bf16 v[68:71], v[160:163], v[208:211], v[68:71]
	v_mfma_f32_16x16x32_bf16 v[64:67], v[168:171], v[208:211], v[64:67]
	s_barrier
; #define PG8_STAGE(bufoff, gbase, voff) do { _Pragma("unroll") for (int _i = 0; _i < 2; ++_i) \
;         __builtin_amdgcn_global_load_lds((const unsigned*)((const char*)(gbase) + (voff)[_i]), (PG8_LAS unsigned*)(lds + (bufoff) + ldsw + _i * 8192), 16, 0, 0); } while (0)
; #define PG8_LDA(dst, b, h) do { _Pragma("unroll") for (int m = 0; m < 4; ++m) _Pragma("unroll") for (int k = 0; k < 2; ++k) dst[m][k] = *(const PG8_LAS bf16x8*)(lds + PG8_SA(b, h) + aoff + m * 2048 + k * 1024); } while (0)
; #define PG8_MMA(ai, bj, At, Bt) do { __builtin_amdgcn_s_setprio(1); _Pragma("unroll") for (int m = 0; m < 4; ++m) _Pragma("unroll") for (int n = 0; n < 2; ++n) _Pragma("unroll") for (int k = 0; k < 2; ++k) \
;         acc[ai][bj][m][n] = __builtin_amdgcn_mfma_f32_16x16x32_bf16(Bt[n][k], At[m][k], acc[ai][bj][m][n], 0, 0, 0); __builtin_amdgcn_s_setprio(0); } while (0)
; #define PG8_WAIT_V(n) asm volatile("s_waitcnt vmcnt(" #n ")" ::: "memory")
; #define PG8_WAIT_L(n) asm volatile("s_waitcnt lgkmcnt(" #n ")" ::: "memory")
; #define PG8_BAR __builtin_amdgcn_s_barrier()
; #define PG8_SCHED __builtin_amdgcn_sched_barrier(0)
; template <class Epi, class Sched, bool ALIGN_EPI = false, bool SP2 = true>
; __device__ __forceinline__ void gemm_phase(PG8_LAS unsigned char* lds, const Gemm g, const Sched& S, const Epi& E) {
;     ...
;             PG8_LDA(At, 1, 1); PG8_STAGE(PG8_SB(1, 0), b3, voffB); PG8_STAGE(PG8_SB(1, 1), b3 + hstep, voffB); PG8_STAGE(PG8_SA(1, 0), a3, voffA);
;             PG8_WAIT_V(8); PG8_WAIT_L(0); PG8_BAR; PG8_MMA(1, 0, At, B0); PG8_MMA(1, 1, At, B1); PG8_BAR; PG8_SCHED;
;     ...
;         }
;         if constexpr (ALIGN_EPI) { if (wr == 0) PG8_BAR; }
	s_setprio 0
	s_mov_b32 m0, s7
	v_lshl_add_u64 v[134:135], v[134:135], 0, s[18:19]
	ds_read_b128 v[172:175], v139 offset:49152
	ds_read_b128 v[176:179], v139 offset:50176
	ds_read_b128 v[180:183], v139 offset:51200
	ds_read_b128 v[184:187], v139 offset:52224
	ds_read_b128 v[188:191], v139 offset:53248
	ds_read_b128 v[200:203], v139 offset:54272
	ds_read_b128 v[204:207], v139 offset:55296
	ds_read_b128 v[208:211], v139 offset:56320
	global_load_lds_dwordx4 v[134:135], off
	v_lshl_add_u64 v[134:135], v[198:199], 0, s[18:19]
	s_mov_b32 m0, s6
	s_nop 0
	global_load_lds_dwordx4 v[134:135], off
	v_lshl_add_u64 v[134:135], s[48:49], 0, v[194:195]
	s_mov_b32 m0, s15
	s_nop 0
	global_load_lds_dwordx4 v[134:135], off
	v_lshl_add_u64 v[134:135], s[48:49], 0, v[128:129]
	s_mov_b32 m0, s14
	s_nop 0
	global_load_lds_dwordx4 v[134:135], off
	v_lshl_add_u64 v[134:135], v[212:213], 0, s[18:19]
	s_mov_b32 m0, s31
	s_nop 0
	global_load_lds_dwordx4 v[134:135], off
	v_lshl_add_u64 v[134:135], v[214:215], 0, s[18:19]
	s_mov_b32 m0, s34
	s_nop 0
	global_load_lds_dwordx4 v[134:135], off
	s_waitcnt vmcnt(8)
	s_waitcnt lgkmcnt(0)
	s_setprio 1
	s_barrier
	v_mfma_f32_16x16x32_bf16 v[60:63], v[140:143], v[172:175], v[60:63]
	v_mfma_f32_16x16x32_bf16 v[56:59], v[148:151], v[172:175], v[56:59]
	v_mfma_f32_16x16x32_bf16 v[52:55], v[140:143], v[180:183], v[52:55]
	v_mfma_f32_16x16x32_bf16 v[44:47], v[148:151], v[180:183], v[44:47]
	v_mfma_f32_16x16x32_bf16 v[36:39], v[140:143], v[188:191], v[36:39]
	v_mfma_f32_16x16x32_bf16 v[28:31], v[148:151], v[188:191], v[28:31]
	v_mfma_f32_16x16x32_bf16 v[20:23], v[140:143], v[204:207], v[20:23]
	v_mfma_f32_16x16x32_bf16 v[12:15], v[148:151], v[204:207], v[12:15]
	v_mfma_f32_16x16x32_bf16 v[60:63], v[144:147], v[176:179], v[60:63]
	v_mfma_f32_16x16x32_bf16 v[56:59], v[152:155], v[176:179], v[56:59]
	v_mfma_f32_16x16x32_bf16 v[52:55], v[144:147], v[184:187], v[52:55]
	v_mfma_f32_16x16x32_bf16 v[44:47], v[152:155], v[184:187], v[44:47]
	v_mfma_f32_16x16x32_bf16 v[36:39], v[144:147], v[200:203], v[36:39]
	v_mfma_f32_16x16x32_bf16 v[28:31], v[152:155], v[200:203], v[28:31]
	v_mfma_f32_16x16x32_bf16 v[20:23], v[144:147], v[208:211], v[20:23]
	v_mfma_f32_16x16x32_bf16 v[12:15], v[152:155], v[208:211], v[12:15]
	v_mfma_f32_16x16x32_bf16 v[48:51], v[156:159], v[172:175], v[48:51]
	v_mfma_f32_16x16x32_bf16 v[40:43], v[164:167], v[172:175], v[40:43]
	v_mfma_f32_16x16x32_bf16 v[32:35], v[156:159], v[180:183], v[32:35]
	v_mfma_f32_16x16x32_bf16 v[24:27], v[164:167], v[180:183], v[24:27]
	v_mfma_f32_16x16x32_bf16 v[16:19], v[156:159], v[188:191], v[16:19]
	v_mfma_f32_16x16x32_bf16 v[8:11], v[164:167], v[188:191], v[8:11]
	v_mfma_f32_16x16x32_bf16 v[4:7], v[156:159], v[204:207], v[4:7]
	v_mfma_f32_16x16x32_bf16 v[0:3], v[164:167], v[204:207], v[0:3]
	v_mfma_f32_16x16x32_bf16 v[48:51], v[160:163], v[176:179], v[48:51]
	v_mfma_f32_16x16x32_bf16 v[40:43], v[168:171], v[176:179], v[40:43]
	v_mfma_f32_16x16x32_bf16 v[32:35], v[160:163], v[184:187], v[32:35]
	v_mfma_f32_16x16x32_bf16 v[24:27], v[168:171], v[184:187], v[24:27]
	v_mfma_f32_16x16x32_bf16 v[16:19], v[160:163], v[200:203], v[16:19]
	v_mfma_f32_16x16x32_bf16 v[8:11], v[168:171], v[200:203], v[8:11]
	v_mfma_f32_16x16x32_bf16 v[4:7], v[160:163], v[208:211], v[4:7]
	v_mfma_f32_16x16x32_bf16 v[0:3], v[168:171], v[208:211], v[0:3]
	s_barrier
	s_setprio 0
	s_movk_i32 s6, 0x100
	s_andn2_b64 vcc, exec, s[46:47]
	s_mov_b64 s[48:49], -1
	s_mov_b64 s[46:47], 0
	s_cbranch_vccz .LBB0_540
	s_and_b64 vcc, exec, s[10:11]
	s_cbranch_vccz .LBB0_543
	s_barrier

; #define PG8_STAGE(bufoff, gbase, voff) do { _Pragma("unroll") for (int _i = 0; _i < 2; ++_i) \
;         __builtin_amdgcn_global_load_lds((const unsigned*)((const char*)(gbase) + (voff)[_i]), (PG8_LAS unsigned*)(lds + (bufoff) + ldsw + _i * 8192), 16, 0, 0); } while (0)
; #define PG8_LDA(dst, b, h) do { _Pragma("unroll") for (int m = 0; m < 4; ++m) _Pragma("unroll") for (int k = 0; k < 2; ++k) dst[m][k] = *(const PG8_LAS bf16x8*)(lds + PG8_SA(b, h) + aoff + m * 2048 + k * 1024); } while (0)
; #define PG8_LDB(dst, b, h) do { _Pragma("unroll") for (int n = 0; n < 2; ++n) _Pragma("unroll") for (int k = 0; k < 2; ++k) dst[n][k] = *(const PG8_LAS bf16x8*)(lds + PG8_SB(b, h) + boff + n * 2048 + k * 1024); } while (0)
; #define PG8_MMA(ai, bj, At, Bt) do { __builtin_amdgcn_s_setprio(1); _Pragma("unroll") for (int m = 0; m < 4; ++m) _Pragma("unroll") for (int n = 0; n < 2; ++n) _Pragma("unroll") for (int k = 0; k < 2; ++k) \
;         acc[ai][bj][m][n] = __builtin_amdgcn_mfma_f32_16x16x32_bf16(Bt[n][k], At[m][k], acc[ai][bj][m][n], 0, 0, 0); __builtin_amdgcn_s_setprio(0); } while (0)
; #define PG8_WAIT_V(n) asm volatile("s_waitcnt vmcnt(" #n ")" ::: "memory")
; #define PG8_WAIT_L(n) asm volatile("s_waitcnt lgkmcnt(" #n ")" ::: "memory")
; template <class Epi, class Sched, bool ALIGN_EPI = false, bool SP2 = true>
; __device__ __forceinline__ void gemm_phase(PG8_LAS unsigned char* lds, const Gemm g, const Sched& S, const Epi& E) {
;     ...
;             const bool last = (t == nt - 2);
;             const char* a1 = cA + (size_t)(t + 1) * kstepA;
;             const char* a2 = last ? nA : cA + (size_t)(t + 2) * kstepA; const char* b2 = last ? nB : cB + (size_t)(t + 2) * kstep;
;             const char* a3 = a2 + kstepA; const char* b3 = b2 + kstep;
;             if (last && has_next) S.a_ready(nxt);
;             if constexpr (SP2) {
;             PG8_LDB(B0, 0, 0); PG8_LDB(B1, 0, 1); PG8_SCHED; PG8_LDA(At, 0, 0); PG8_STAGE(PG8_SA(1, 1), a1 + hstepA, voffA);
;             PG8_WAIT_V(8); PG8_WAIT_L(0); PG8_BAR; PG8_MMA(0, 0, At, B0); PG8_MMA(0, 1, At, B1); PG8_BAR; PG8_SCHED;
;             PG8_LDA(At, 0, 1); PG8_STAGE(PG8_SB(0, 0), b2, voffB); PG8_STAGE(PG8_SB(0, 1), b2 + hstep, voffB); PG8_STAGE(PG8_SA(0, 0), a2, voffA);
;             PG8_WAIT_V(8); PG8_WAIT_L(0); PG8_BAR; PG8_MMA(1, 0, At, B0); PG8_MMA(1, 1, At, B1); PG8_BAR; PG8_SCHED;
.LBB0_745:
	s_add_u32 s4, s50, 0xfffc0080
	s_addc_u32 s5, s51, -1
	s_add_i32 s14, 0, 0x10000
	s_cmp_eq_u32 s47, 12
	s_cselect_b32 s85, s16, s5
	s_cselect_b32 s84, s17, s4
	s_cselect_b32 s53, s25, s7
	s_cselect_b32 s52, s41, s6
	s_add_i32 s4, 0, 0x14000
	v_add_u32_e32 v146, s14, v173
	v_add_u32_e32 v162, s4, v173
	ds_read_b128 v[134:137], v146
	ds_read_b128 v[138:141], v146 offset:1024
	ds_read_b128 v[142:145], v146 offset:2048
	ds_read_b128 v[146:149], v146 offset:3072
	ds_read_b128 v[150:153], v162
	ds_read_b128 v[154:157], v162 offset:1024
	ds_read_b128 v[158:161], v162 offset:2048
	ds_read_b128 v[162:165], v162 offset:3072
	v_lshl_add_u64 v[170:171], s[50:51], 0, v[130:131]
	s_add_i32 m0, s31, 0xc000
	ds_read_b128 v[166:169], v175
	ds_read_b128 v[176:179], v175 offset:1024
	ds_read_b128 v[180:183], v175 offset:2048
	ds_read_b128 v[184:187], v175 offset:3072
	ds_read_b128 v[188:191], v175 offset:4096
	ds_read_b128 v[200:203], v175 offset:5120
	ds_read_b128 v[204:207], v175 offset:6144
	ds_read_b128 v[208:211], v175 offset:7168
	global_load_lds_dwordx4 v[170:171], off
	v_lshl_add_u64 v[170:171], s[50:51], 0, v[132:133]
	s_add_i32 m0, s31, 0xe000
	s_nop 0
	global_load_lds_dwordx4 v[170:171], off
	s_waitcnt vmcnt(8)
	s_waitcnt lgkmcnt(0)
	s_setprio 1
	s_barrier
	v_mfma_f32_16x16x32_bf16 v[124:127], v[134:137], v[166:169], v[124:127]
	v_mfma_f32_16x16x32_bf16 v[120:123], v[142:145], v[166:169], v[120:123]
	v_mfma_f32_16x16x32_bf16 v[108:111], v[134:137], v[180:183], v[108:111]
	v_mfma_f32_16x16x32_bf16 v[104:107], v[142:145], v[180:183], v[104:107]
	v_mfma_f32_16x16x32_bf16 v[92:95], v[134:137], v[188:191], v[92:95]
	v_mfma_f32_16x16x32_bf16 v[88:91], v[142:145], v[188:191], v[88:91]
	v_mfma_f32_16x16x32_bf16 v[76:79], v[134:137], v[204:207], v[76:79]
	v_mfma_f32_16x16x32_bf16 v[72:75], v[142:145], v[204:207], v[72:75]
	v_mfma_f32_16x16x32_bf16 v[124:127], v[138:141], v[176:179], v[124:127]
	v_mfma_f32_16x16x32_bf16 v[120:123], v[146:149], v[176:179], v[120:123]
	v_mfma_f32_16x16x32_bf16 v[108:111], v[138:141], v[184:187], v[108:111]
	v_mfma_f32_16x16x32_bf16 v[104:107], v[146:149], v[184:187], v[104:107]
	v_mfma_f32_16x16x32_bf16 v[92:95], v[138:141], v[200:203], v[92:95]
	v_mfma_f32_16x16x32_bf16 v[88:91], v[146:149], v[200:203], v[88:91]
	v_mfma_f32_16x16x32_bf16 v[76:79], v[138:141], v[208:211], v[76:79]
	v_mfma_f32_16x16x32_bf16 v[72:75], v[146:149], v[208:211], v[72:75]
	v_mfma_f32_16x16x32_bf16 v[116:119], v[150:153], v[166:169], v[116:119]
	v_mfma_f32_16x16x32_bf16 v[112:115], v[158:161], v[166:169], v[112:115]
	v_mfma_f32_16x16x32_bf16 v[100:103], v[150:153], v[180:183], v[100:103]
	v_mfma_f32_16x16x32_bf16 v[96:99], v[158:161], v[180:183], v[96:99]
	v_mfma_f32_16x16x32_bf16 v[84:87], v[150:153], v[188:191], v[84:87]
	v_mfma_f32_16x16x32_bf16 v[80:83], v[158:161], v[188:191], v[80:83]
	v_mfma_f32_16x16x32_bf16 v[68:71], v[150:153], v[204:207], v[68:71]
	v_mfma_f32_16x16x32_bf16 v[64:67], v[158:161], v[204:207], v[64:67]
	v_mfma_f32_16x16x32_bf16 v[116:119], v[154:157], v[176:179], v[116:119]
	v_mfma_f32_16x16x32_bf16 v[112:115], v[162:165], v[176:179], v[112:115]
	v_mfma_f32_16x16x32_bf16 v[100:103], v[154:157], v[184:187], v[100:103]
	v_mfma_f32_16x16x32_bf16 v[96:99], v[162:165], v[184:187], v[96:99]
	v_mfma_f32_16x16x32_bf16 v[84:87], v[154:157], v[200:203], v[84:87]
	v_mfma_f32_16x16x32_bf16 v[80:83], v[162:165], v[200:203], v[80:83]
	v_mfma_f32_16x16x32_bf16 v[68:71], v[154:157], v[208:211], v[68:71]
	v_mfma_f32_16x16x32_bf16 v[64:67], v[162:165], v[208:211], v[64:67]
	s_barrier
	s_setprio 0
	s_add_i32 s5, s14, s30
	v_lshl_add_u64 v[170:171], s[52:53], 0, v[194:195]
	s_mov_b32 m0, s5
	ds_read_b128 v[166:169], v175 offset:16384
	ds_read_b128 v[176:179], v175 offset:17408
	ds_read_b128 v[180:183], v175 offset:18432
	ds_read_b128 v[184:187], v175 offset:19456
	ds_read_b128 v[188:191], v175 offset:20480
	ds_read_b128 v[200:203], v175 offset:21504
	ds_read_b128 v[204:207], v175 offset:22528
	ds_read_b128 v[208:211], v175 offset:23552
	global_load_lds_dwordx4 v[170:171], off
	s_add_i32 m0, s5, 0x2000
	s_add_u32 s14, s52, 0x40000
	v_lshl_add_u64 v[198:199], s[52:53], 0, v[128:129]
	s_addc_u32 s15, s53, 0
	s_add_i32 s4, s4, s30
	global_load_lds_dwordx4 v[198:199], off
	v_lshl_add_u64 v[212:213], s[14:15], 0, v[194:195]
	s_mov_b32 m0, s4
	v_lshl_add_u64 v[214:215], s[84:85], 0, v[128:129]
	global_load_lds_dwordx4 v[212:213], off
	v_lshl_add_u64 v[212:213], s[14:15], 0, v[128:129]
	s_add_i32 m0, s4, 0x2000
	s_nop 0
	global_load_lds_dwordx4 v[212:213], off
	v_lshl_add_u64 v[212:213], s[84:85], 0, v[194:195]
	s_mov_b32 m0, s31
	s_nop 0
	global_load_lds_dwordx4 v[212:213], off
	s_mov_b32 m0, s34
	s_nop 0
	global_load_lds_dwordx4 v[214:215], off
	s_waitcnt vmcnt(8)
	s_waitcnt lgkmcnt(0)
	s_setprio 1
	s_barrier
; #define PG8_STAGE(bufoff, gbase, voff) do { _Pragma("unroll") for (int _i = 0; _i < 2; ++_i) \
;         __builtin_amdgcn_global_load_lds((const unsigned*)((const char*)(gbase) + (voff)[_i]), (PG8_LAS unsigned*)(lds + (bufoff) + ldsw + _i * 8192), 16, 0, 0); } while (0)
; #define PG8_LDA(dst, b, h) do { _Pragma("unroll") for (int m = 0; m < 4; ++m) _Pragma("unroll") for (int k = 0; k < 2; ++k) dst[m][k] = *(const PG8_LAS bf16x8*)(lds + PG8_SA(b, h) + aoff + m * 2048 + k * 1024); } while (0)
; #define PG8_LDB(dst, b, h) do { _Pragma("unroll") for (int n = 0; n < 2; ++n) _Pragma("unroll") for (int k = 0; k < 2; ++k) dst[n][k] = *(const PG8_LAS bf16x8*)(lds + PG8_SB(b, h) + boff + n * 2048 + k * 1024); } while (0)
; #define PG8_MMA(ai, bj, At, Bt) do { __builtin_amdgcn_s_setprio(1); _Pragma("unroll") for (int m = 0; m < 4; ++m) _Pragma("unroll") for (int n = 0; n < 2; ++n) _Pragma("unroll") for (int k = 0; k < 2; ++k) \
;         acc[ai][bj][m][n] = __builtin_amdgcn_mfma_f32_16x16x32_bf16(Bt[n][k], At[m][k], acc[ai][bj][m][n], 0, 0, 0); __builtin_amdgcn_s_setprio(0); } while (0)
; #define PG8_WAIT_V(n) asm volatile("s_waitcnt vmcnt(" #n ")" ::: "memory")
; #define PG8_WAIT_L(n) asm volatile("s_waitcnt lgkmcnt(" #n ")" ::: "memory")
; #define PG8_BAR __builtin_amdgcn_s_barrier()
; #define PG8_SCHED __builtin_amdgcn_sched_barrier(0)
; template <class Epi, class Sched, bool ALIGN_EPI = false, bool SP2 = true>
; __device__ __forceinline__ void gemm_phase(PG8_LAS unsigned char* lds, const Gemm g, const Sched& S, const Epi& E) {
;     ...
;             PG8_WAIT_V(8); PG8_WAIT_L(0); PG8_BAR; PG8_MMA(1, 0, At, B0); PG8_MMA(1, 1, At, B1); PG8_BAR; PG8_SCHED;
;             PG8_LDB(B0, 1, 0); PG8_LDB(B1, 1, 1); PG8_SCHED; PG8_LDA(At, 1, 0); PG8_STAGE(PG8_SA(0, 1), a2 + hstepA, voffA);
;             PG8_WAIT_V(8); PG8_WAIT_L(0); PG8_BAR; PG8_MMA(0, 0, At, B0); PG8_MMA(0, 1, At, B1); PG8_BAR; PG8_SCHED;
;             PG8_LDA(At, 1, 1); PG8_STAGE(PG8_SB(1, 0), b3, voffB); PG8_STAGE(PG8_SB(1, 1), b3 + hstep, voffB); PG8_STAGE(PG8_SA(1, 0), a3, voffA);
;             PG8_WAIT_V(8); PG8_WAIT_L(0); PG8_BAR; PG8_MMA(1, 0, At, B0); PG8_MMA(1, 1, At, B1); PG8_BAR; PG8_SCHED;
	v_mfma_f32_16x16x32_bf16 v[60:63], v[134:137], v[166:169], v[60:63]
	v_mfma_f32_16x16x32_bf16 v[56:59], v[142:145], v[166:169], v[56:59]
	v_mfma_f32_16x16x32_bf16 v[44:47], v[134:137], v[180:183], v[44:47]
	v_mfma_f32_16x16x32_bf16 v[40:43], v[142:145], v[180:183], v[40:43]
	v_mfma_f32_16x16x32_bf16 v[28:31], v[134:137], v[188:191], v[28:31]
	v_mfma_f32_16x16x32_bf16 v[24:27], v[142:145], v[188:191], v[24:27]
	v_mfma_f32_16x16x32_bf16 v[12:15], v[134:137], v[204:207], v[12:15]
	v_mfma_f32_16x16x32_bf16 v[8:11], v[142:145], v[204:207], v[8:11]
	v_mfma_f32_16x16x32_bf16 v[60:63], v[138:141], v[176:179], v[60:63]
	v_mfma_f32_16x16x32_bf16 v[56:59], v[146:149], v[176:179], v[56:59]
	v_mfma_f32_16x16x32_bf16 v[44:47], v[138:141], v[184:187], v[44:47]
	v_mfma_f32_16x16x32_bf16 v[40:43], v[146:149], v[184:187], v[40:43]
	v_mfma_f32_16x16x32_bf16 v[28:31], v[138:141], v[200:203], v[28:31]
	v_mfma_f32_16x16x32_bf16 v[24:27], v[146:149], v[200:203], v[24:27]
	v_mfma_f32_16x16x32_bf16 v[12:15], v[138:141], v[208:211], v[12:15]
	v_mfma_f32_16x16x32_bf16 v[8:11], v[146:149], v[208:211], v[8:11]
	v_mfma_f32_16x16x32_bf16 v[52:55], v[150:153], v[166:169], v[52:55]
	v_mfma_f32_16x16x32_bf16 v[48:51], v[158:161], v[166:169], v[48:51]
	v_mfma_f32_16x16x32_bf16 v[36:39], v[150:153], v[180:183], v[36:39]
	v_mfma_f32_16x16x32_bf16 v[32:35], v[158:161], v[180:183], v[32:35]
	v_mfma_f32_16x16x32_bf16 v[20:23], v[150:153], v[188:191], v[20:23]
	v_mfma_f32_16x16x32_bf16 v[16:19], v[158:161], v[188:191], v[16:19]
	v_mfma_f32_16x16x32_bf16 v[4:7], v[150:153], v[204:207], v[4:7]
	v_mfma_f32_16x16x32_bf16 v[0:3], v[158:161], v[204:207], v[0:3]
	v_mfma_f32_16x16x32_bf16 v[52:55], v[154:157], v[176:179], v[52:55]
	v_mfma_f32_16x16x32_bf16 v[48:51], v[162:165], v[176:179], v[48:51]
	v_mfma_f32_16x16x32_bf16 v[36:39], v[154:157], v[184:187], v[36:39]
	v_mfma_f32_16x16x32_bf16 v[32:35], v[162:165], v[184:187], v[32:35]
	v_mfma_f32_16x16x32_bf16 v[20:23], v[154:157], v[200:203], v[20:23]
	v_mfma_f32_16x16x32_bf16 v[16:19], v[162:165], v[200:203], v[16:19]
	v_mfma_f32_16x16x32_bf16 v[4:7], v[154:157], v[208:211], v[4:7]
	v_mfma_f32_16x16x32_bf16 v[0:3], v[162:165], v[208:211], v[0:3]
	s_barrier
	s_setprio 0
	s_add_i32 s4, 0, 0x18000
	s_add_i32 s5, 0, 0x1c000
	v_add_u32_e32 v146, s4, v173
	v_add_u32_e32 v162, s5, v173
	ds_read_b128 v[134:137], v146
	ds_read_b128 v[138:141], v146 offset:1024
	ds_read_b128 v[142:145], v146 offset:2048
	ds_read_b128 v[146:149], v146 offset:3072
	ds_read_b128 v[150:153], v162
	ds_read_b128 v[154:157], v162 offset:1024
	ds_read_b128 v[158:161], v162 offset:2048
	ds_read_b128 v[162:165], v162 offset:3072
	s_add_u32 s14, s84, 0x40000
	s_addc_u32 s15, s85, 0
	s_mov_b32 m0, s35
	v_lshl_add_u64 v[216:217], s[14:15], 0, v[194:195]
	ds_read_b128 v[166:169], v175 offset:32768
	ds_read_b128 v[176:179], v175 offset:33792
	ds_read_b128 v[180:183], v175 offset:34816
	ds_read_b128 v[184:187], v175 offset:35840
	ds_read_b128 v[188:191], v175 offset:36864
	ds_read_b128 v[200:203], v175 offset:37888
	ds_read_b128 v[204:207], v175 offset:38912
	ds_read_b128 v[208:211], v175 offset:39936
	global_load_lds_dwordx4 v[216:217], off
	v_lshl_add_u64 v[216:217], s[14:15], 0, v[128:129]
	s_mov_b32 m0, s49
	s_nop 0
	global_load_lds_dwordx4 v[216:217], off
	s_waitcnt vmcnt(8)
	s_waitcnt lgkmcnt(0)
	s_setprio 1
	s_barrier
	v_mfma_f32_16x16x32_bf16 v[124:127], v[134:137], v[166:169], v[124:127]
	v_mfma_f32_16x16x32_bf16 v[120:123], v[142:145], v[166:169], v[120:123]
	v_mfma_f32_16x16x32_bf16 v[108:111], v[134:137], v[180:183], v[108:111]
	v_mfma_f32_16x16x32_bf16 v[104:107], v[142:145], v[180:183], v[104:107]
	v_mfma_f32_16x16x32_bf16 v[92:95], v[134:137], v[188:191], v[92:95]
	v_mfma_f32_16x16x32_bf16 v[88:91], v[142:145], v[188:191], v[88:91]
	v_mfma_f32_16x16x32_bf16 v[76:79], v[134:137], v[204:207], v[76:79]
	v_mfma_f32_16x16x32_bf16 v[72:75], v[142:145], v[204:207], v[72:75]
	v_mfma_f32_16x16x32_bf16 v[124:127], v[138:141], v[176:179], v[124:127]
	v_mfma_f32_16x16x32_bf16 v[120:123], v[146:149], v[176:179], v[120:123]
	v_mfma_f32_16x16x32_bf16 v[108:111], v[138:141], v[184:187], v[108:111]
	v_mfma_f32_16x16x32_bf16 v[104:107], v[146:149], v[184:187], v[104:107]
	v_mfma_f32_16x16x32_bf16 v[92:95], v[138:141], v[200:203], v[92:95]
	v_mfma_f32_16x16x32_bf16 v[88:91], v[146:149], v[200:203], v[88:91]
	v_mfma_f32_16x16x32_bf16 v[76:79], v[138:141], v[208:211], v[76:79]
	v_mfma_f32_16x16x32_bf16 v[72:75], v[146:149], v[208:211], v[72:75]
	v_mfma_f32_16x16x32_bf16 v[116:119], v[150:153], v[166:169], v[116:119]
	v_mfma_f32_16x16x32_bf16 v[112:115], v[158:161], v[166:169], v[112:115]
	v_mfma_f32_16x16x32_bf16 v[100:103], v[150:153], v[180:183], v[100:103]
	v_mfma_f32_16x16x32_bf16 v[96:99], v[158:161], v[180:183], v[96:99]
	v_mfma_f32_16x16x32_bf16 v[84:87], v[150:153], v[188:191], v[84:87]
	v_mfma_f32_16x16x32_bf16 v[80:83], v[158:161], v[188:191], v[80:83]
	v_mfma_f32_16x16x32_bf16 v[68:71], v[150:153], v[204:207], v[68:71]
	v_mfma_f32_16x16x32_bf16 v[64:67], v[158:161], v[204:207], v[64:67]
	v_mfma_f32_16x16x32_bf16 v[116:119], v[154:157], v[176:179], v[116:119]
	v_mfma_f32_16x16x32_bf16 v[112:115], v[162:165], v[176:179], v[112:115]
	v_mfma_f32_16x16x32_bf16 v[100:103], v[154:157], v[184:187], v[100:103]
	v_mfma_f32_16x16x32_bf16 v[96:99], v[162:165], v[184:187], v[96:99]
	v_mfma_f32_16x16x32_bf16 v[84:87], v[154:157], v[200:203], v[84:87]
	v_mfma_f32_16x16x32_bf16 v[80:83], v[162:165], v[200:203], v[80:83]
	v_mfma_f32_16x16x32_bf16 v[68:71], v[154:157], v[208:211], v[68:71]
	v_mfma_f32_16x16x32_bf16 v[64:67], v[162:165], v[208:211], v[64:67]
	s_barrier
; #define PG8_STAGE(bufoff, gbase, voff) do { _Pragma("unroll") for (int _i = 0; _i < 2; ++_i) \
;         __builtin_amdgcn_global_load_lds((const unsigned*)((const char*)(gbase) + (voff)[_i]), (PG8_LAS unsigned*)(lds + (bufoff) + ldsw + _i * 8192), 16, 0, 0); } while (0)
; #define PG8_LDA(dst, b, h) do { _Pragma("unroll") for (int m = 0; m < 4; ++m) _Pragma("unroll") for (int k = 0; k < 2; ++k) dst[m][k] = *(const PG8_LAS bf16x8*)(lds + PG8_SA(b, h) + aoff + m * 2048 + k * 1024); } while (0)
; #define PG8_MMA(ai, bj, At, Bt) do { __builtin_amdgcn_s_setprio(1); _Pragma("unroll") for (int m = 0; m < 4; ++m) _Pragma("unroll") for (int n = 0; n < 2; ++n) _Pragma("unroll") for (int k = 0; k < 2; ++k) \
;         acc[ai][bj][m][n] = __builtin_amdgcn_mfma_f32_16x16x32_bf16(Bt[n][k], At[m][k], acc[ai][bj][m][n], 0, 0, 0); __builtin_amdgcn_s_setprio(0); } while (0)
; #define PG8_WAIT_V(n) asm volatile("s_waitcnt vmcnt(" #n ")" ::: "memory")
; #define PG8_WAIT_L(n) asm volatile("s_waitcnt lgkmcnt(" #n ")" ::: "memory")
; #define PG8_BAR __builtin_amdgcn_s_barrier()
; #define PG8_SCHED __builtin_amdgcn_sched_barrier(0)
; template <class Epi, class Sched, bool ALIGN_EPI = false, bool SP2 = true>
; __device__ __forceinline__ void gemm_phase(PG8_LAS unsigned char* lds, const Gemm g, const Sched& S, const Epi& E) {
;     ...
;             PG8_LDA(At, 1, 1); PG8_STAGE(PG8_SB(1, 0), b3, voffB); PG8_STAGE(PG8_SB(1, 1), b3 + hstep, voffB); PG8_STAGE(PG8_SA(1, 0), a3, voffA);
;             PG8_WAIT_V(8); PG8_WAIT_L(0); PG8_BAR; PG8_MMA(1, 0, At, B0); PG8_MMA(1, 1, At, B1); PG8_BAR; PG8_SCHED;
;     ...
;         }
;         if constexpr (ALIGN_EPI) { if (wr == 0) PG8_BAR; }
	s_setprio 0
	s_add_i32 s4, s4, s30
	v_lshl_add_u64 v[170:171], v[170:171], 0, s[18:19]
	s_mov_b32 m0, s4
	ds_read_b128 v[166:169], v175 offset:49152
	ds_read_b128 v[176:179], v175 offset:50176
	ds_read_b128 v[180:183], v175 offset:51200
	ds_read_b128 v[184:187], v175 offset:52224
	ds_read_b128 v[188:191], v175 offset:53248
	ds_read_b128 v[200:203], v175 offset:54272
	ds_read_b128 v[204:207], v175 offset:55296
	ds_read_b128 v[208:211], v175 offset:56320
	global_load_lds_dwordx4 v[170:171], off
	s_add_i32 m0, s4, 0x2000
	s_add_u32 s14, s52, 0x40080
	v_lshl_add_u64 v[170:171], v[198:199], 0, s[18:19]
	s_addc_u32 s15, s53, 0
	s_add_i32 s4, s5, s30
	global_load_lds_dwordx4 v[170:171], off
	v_lshl_add_u64 v[170:171], s[14:15], 0, v[194:195]
	s_mov_b32 m0, s4
	s_nop 0
	global_load_lds_dwordx4 v[170:171], off
	v_lshl_add_u64 v[170:171], s[14:15], 0, v[128:129]
	s_add_i32 m0, s4, 0x2000
	s_nop 0
	global_load_lds_dwordx4 v[170:171], off
	v_lshl_add_u64 v[170:171], v[212:213], 0, s[18:19]
	s_mov_b32 m0, s57
	s_nop 0
	global_load_lds_dwordx4 v[170:171], off
	v_lshl_add_u64 v[170:171], v[214:215], 0, s[18:19]
	s_mov_b32 m0, s59
	s_nop 0
	global_load_lds_dwordx4 v[170:171], off
	s_waitcnt vmcnt(8)
	s_waitcnt lgkmcnt(0)
	s_setprio 1
	s_barrier
	v_mfma_f32_16x16x32_bf16 v[60:63], v[134:137], v[166:169], v[60:63]
	v_mfma_f32_16x16x32_bf16 v[56:59], v[142:145], v[166:169], v[56:59]
	v_mfma_f32_16x16x32_bf16 v[44:47], v[134:137], v[180:183], v[44:47]
	v_mfma_f32_16x16x32_bf16 v[40:43], v[142:145], v[180:183], v[40:43]
	v_mfma_f32_16x16x32_bf16 v[28:31], v[134:137], v[188:191], v[28:31]
	v_mfma_f32_16x16x32_bf16 v[24:27], v[142:145], v[188:191], v[24:27]
	v_mfma_f32_16x16x32_bf16 v[12:15], v[134:137], v[204:207], v[12:15]
	v_mfma_f32_16x16x32_bf16 v[8:11], v[142:145], v[204:207], v[8:11]
	v_mfma_f32_16x16x32_bf16 v[60:63], v[138:141], v[176:179], v[60:63]
	v_mfma_f32_16x16x32_bf16 v[56:59], v[146:149], v[176:179], v[56:59]
	v_mfma_f32_16x16x32_bf16 v[44:47], v[138:141], v[184:187], v[44:47]
	v_mfma_f32_16x16x32_bf16 v[40:43], v[146:149], v[184:187], v[40:43]
	v_mfma_f32_16x16x32_bf16 v[28:31], v[138:141], v[200:203], v[28:31]
	v_mfma_f32_16x16x32_bf16 v[24:27], v[146:149], v[200:203], v[24:27]
	v_mfma_f32_16x16x32_bf16 v[12:15], v[138:141], v[208:211], v[12:15]
	v_mfma_f32_16x16x32_bf16 v[8:11], v[146:149], v[208:211], v[8:11]
	v_mfma_f32_16x16x32_bf16 v[52:55], v[150:153], v[166:169], v[52:55]
	v_mfma_f32_16x16x32_bf16 v[48:51], v[158:161], v[166:169], v[48:51]
	v_mfma_f32_16x16x32_bf16 v[36:39], v[150:153], v[180:183], v[36:39]
	v_mfma_f32_16x16x32_bf16 v[32:35], v[158:161], v[180:183], v[32:35]
	v_mfma_f32_16x16x32_bf16 v[20:23], v[150:153], v[188:191], v[20:23]
	v_mfma_f32_16x16x32_bf16 v[16:19], v[158:161], v[188:191], v[16:19]
	v_mfma_f32_16x16x32_bf16 v[4:7], v[150:153], v[204:207], v[4:7]
	v_mfma_f32_16x16x32_bf16 v[0:3], v[158:161], v[204:207], v[0:3]
	v_mfma_f32_16x16x32_bf16 v[52:55], v[154:157], v[176:179], v[52:55]
	v_mfma_f32_16x16x32_bf16 v[48:51], v[162:165], v[176:179], v[48:51]
	v_mfma_f32_16x16x32_bf16 v[36:39], v[154:157], v[184:187], v[36:39]
	v_mfma_f32_16x16x32_bf16 v[32:35], v[162:165], v[184:187], v[32:35]
	v_mfma_f32_16x16x32_bf16 v[20:23], v[154:157], v[200:203], v[20:23]
	v_mfma_f32_16x16x32_bf16 v[16:19], v[162:165], v[200:203], v[16:19]
	v_mfma_f32_16x16x32_bf16 v[4:7], v[154:157], v[208:211], v[4:7]
	v_mfma_f32_16x16x32_bf16 v[0:3], v[162:165], v[208:211], v[0:3]
	s_barrier
	s_setprio 0
	s_add_i32 s47, s47, 2
	s_add_u32 s50, s50, 0x100
	s_addc_u32 s51, s51, 0
	s_add_u32 s6, s6, 0x100
	s_addc_u32 s7, s7, 0
	s_cmp_gt_u32 s47, 13
	s_cbranch_scc0 .LBB0_745
	s_and_b64 vcc, exec, s[20:21]
	s_cbranch_vccz .LBB0_748
	s_barrier
